# input-projection epilogues (RoPE ladder): q/k/v/gate stores without nt, so the per-step vmcnt(0) before the next cos/sin use waits for an L2 ack instead of a write-through ack
# speedup vs baseline: 1.0185x; 1.0185x over previous
.LBB0_165:
	v_mov_b64_e32 v[124:125], s[76:77]
	v_mad_i64_i32 v[124:125], s[8:9], v166, s92, v[124:125]
	s_or_b32 s8, s22, 0x80
	s_cmp_lt_i32 s8, s89
	s_cselect_b64 s[8:9], -1, 0
	v_cvt_pk_bf16_f32 v134, v136, v137
	v_cvt_pk_bf16_f32 v135, v138, v139
	v_cvt_pk_bf16_f32 v136, v140, v141
	v_cvt_pk_bf16_f32 v137, v142, v143
	v_lshl_add_u64 v[124:125], v[164:165], 1, v[124:125]
	s_and_b64 s[8:9], s[30:31], s[8:9]
	global_store_dwordx4 v[124:125], v[134:137], off
	v_pk_mul_f32 v[140:141], v[114:115], v[120:121]
	s_andn2_b64 vcc, exec, s[8:9]
	v_pk_mul_f32 v[136:137], v[118:119], v[120:121]
	v_pk_mul_f32 v[134:135], v[116:117], v[168:169]
	v_pk_mul_f32 v[138:139], v[112:113], v[168:169]
	s_cbranch_vccnz .LBB0_173
	v_and_b32_e32 v121, 64, v195
	v_xor_b32_e32 v120, 16, v195
	v_add_u32_e32 v121, 64, v121
	v_cmp_lt_i32_e32 vcc, v120, v121
	s_nop 1
	v_cndmask_b32_e32 v120, v195, v120, vcc
	v_lshlrev_b32_e32 v120, 2, v120
	s_waitcnt lgkmcnt(0)
	ds_bpermute_b32 v170, v120, v134
	ds_bpermute_b32 v174, v120, v138
	ds_bpermute_b32 v171, v120, v135
	ds_bpermute_b32 v175, v120, v139
	ds_bpermute_b32 v142, v120, v136
	ds_bpermute_b32 v178, v120, v140
	ds_bpermute_b32 v143, v120, v137
	ds_bpermute_b32 v179, v120, v141
	s_and_saveexec_b64 s[8:9], s[0:1]
	s_cbranch_execz .LBB0_172
	v_lshlrev_b32_e32 v120, 2, v152
	global_load_dwordx4 v[198:201], v120, s[64:65]
	global_load_dwordx4 v[202:205], v120, s[44:45]
	global_load_dwordx4 v[206:209], v120, s[64:65] offset:16
	global_load_dwordx4 v[210:213], v120, s[44:45] offset:16
	s_waitcnt vmcnt(0)
	v_pk_mul_f32 v[120:121], v[136:137], v[200:201]
	v_pk_mul_f32 v[130:131], v[134:135], v[198:199]
	s_waitcnt lgkmcnt(5)
	v_pk_mul_f32 v[172:173], v[202:203], v[170:171]
	s_waitcnt lgkmcnt(1)
	v_pk_mul_f32 v[176:177], v[204:205], v[142:143]
	v_pk_mul_f32 v[142:143], v[140:141], v[208:209]
	v_pk_mul_f32 v[170:171], v[138:139], v[206:207]
	v_pk_mul_f32 v[174:175], v[210:211], v[174:175]
	s_waitcnt lgkmcnt(0)
	v_pk_mul_f32 v[178:179], v[212:213], v[178:179]
	s_and_saveexec_b64 s[10:11], s[4:5]
	s_xor_b64 s[10:11], exec, s[10:11]
	v_pk_add_f32 v[136:137], v[120:121], v[176:177]
	v_pk_add_f32 v[134:135], v[130:131], v[172:173]
	v_pk_add_f32 v[140:141], v[142:143], v[178:179]
	v_pk_add_f32 v[138:139], v[170:171], v[174:175]
	s_andn2_saveexec_b64 s[10:11], s[10:11]
	v_sub_f32_e32 v137, v121, v177
	v_sub_f32_e32 v136, v120, v176
	v_sub_f32_e32 v135, v131, v173
	v_sub_f32_e32 v134, v130, v172
	v_sub_f32_e32 v141, v143, v179
	v_sub_f32_e32 v140, v142, v178
	v_sub_f32_e32 v139, v171, v175
	v_sub_f32_e32 v138, v170, v174
	s_or_b64 exec, exec, s[10:11]

.LBB0_173:
	v_cvt_pk_bf16_f32 v134, v134, v135
	v_cvt_pk_bf16_f32 v135, v136, v137
	v_cvt_pk_bf16_f32 v136, v138, v139
	v_cvt_pk_bf16_f32 v137, v140, v141
	s_mov_b64 s[8:9], 0
	global_store_dwordx4 v[124:125], v[134:137], off offset:256
.LBB0_174:
	s_and_b64 vcc, exec, s[8:9]
	v_lshlrev_b32_e32 v152, 1, v154
	s_cbranch_vccz .LBB0_176
	v_pk_mul_f32 v[116:117], v[116:117], v[168:169]
	v_mov_b32_e32 v120, v168
	v_mov_b32_e32 v121, v168
	v_mul_f32_e32 v116, 0xbfb8aa3b, v116
	v_pk_mul_f32 v[124:125], v[126:127], v[120:121]
	v_exp_f32_e32 v126, v116
	v_mul_f32_e32 v116, 0xbfb8aa3b, v117
	v_exp_f32_e32 v127, v116
	v_pk_mul_f32 v[116:117], v[122:123], v[120:121]
	v_add_f32_e32 v122, 1.0, v126
	v_pk_mul_f32 v[118:119], v[118:119], v[120:121]
	v_add_f32_e32 v123, 1.0, v127
	v_rcp_f32_e32 v122, v122
	v_rcp_f32_e32 v123, v123
	v_mul_f32_e32 v118, 0xbfb8aa3b, v118
	v_exp_f32_e32 v118, v118
	v_mul_f32_e32 v119, 0xbfb8aa3b, v119
	v_exp_f32_e32 v119, v119
	v_pk_mul_f32 v[114:115], v[114:115], v[120:121]
	v_pk_mul_f32 v[120:121], v[112:113], v[168:169]
	v_pk_mul_f32 v[112:113], v[132:133], v[122:123]
	v_mul_f32_e32 v114, 0xbfb8aa3b, v114
	v_cvt_pk_bf16_f32 v112, v112, v113
	v_add_f32_e32 v113, 1.0, v118
	v_rcp_f32_e32 v118, v113
	v_add_f32_e32 v113, 1.0, v119
	v_rcp_f32_e32 v119, v113
	v_mul_f32_e32 v113, 0xbfb8aa3b, v120
	v_exp_f32_e32 v113, v113
	v_mul_f32_e32 v120, 0xbfb8aa3b, v121
	v_exp_f32_e32 v121, v120
	v_exp_f32_e32 v114, v114
	v_mul_f32_e32 v115, 0xbfb8aa3b, v115
	v_exp_f32_e32 v115, v115
	v_add_f32_e32 v113, 1.0, v113
	v_rcp_f32_e32 v120, v113
	v_add_f32_e32 v113, 1.0, v121
	v_rcp_f32_e32 v121, v113
	v_add_f32_e32 v113, 1.0, v114
	v_rcp_f32_e32 v122, v113
	v_add_f32_e32 v113, 1.0, v115
	v_rcp_f32_e32 v123, v113
	v_pk_mul_f32 v[114:115], v[128:129], v[120:121]
	v_ashrrev_i32_e32 v167, 31, v166
	v_cvt_pk_bf16_f32 v114, v114, v115
	v_pk_mul_f32 v[116:117], v[116:117], v[122:123]
	s_lshl_b32 s8, s86, 1
	v_cvt_pk_bf16_f32 v115, v116, v117
	v_lshlrev_b64 v[116:117], 10, v[166:167]
	v_lshl_add_u64 v[116:117], s[42:43], 0, v[116:117]
	v_lshl_add_u64 v[116:117], v[116:117], 0, s[22:23]
	s_mov_b32 s9, s23
	v_pk_mul_f32 v[118:119], v[124:125], v[118:119]
	v_lshl_add_u64 v[116:117], v[116:117], 0, s[8:9]
	v_cvt_pk_bf16_f32 v113, v118, v119
	v_lshl_add_u64 v[116:117], v[116:117], 0, v[152:153]
	global_store_dwordx4 v[116:117], v[112:115], off offset:-768

.LBB0_186:
	v_mov_b64_e32 v[108:109], s[76:77]
	s_or_b32 s37, s22, 0x80
	v_mad_i64_i32 v[108:109], s[70:71], v128, s92, v[108:109]
	s_cmp_lt_i32 s37, s89
	s_cselect_b64 s[70:71], -1, 0
	v_cvt_pk_bf16_f32 v118, v120, v121
	v_cvt_pk_bf16_f32 v119, v122, v123
	v_cvt_pk_bf16_f32 v120, v124, v125
	v_cvt_pk_bf16_f32 v121, v126, v127
	v_lshl_add_u64 v[108:109], v[164:165], 1, v[108:109]
	s_and_b64 s[70:71], s[30:31], s[70:71]
	global_store_dwordx4 v[108:109], v[118:121], off
	v_pk_mul_f32 v[124:125], v[98:99], v[104:105]
	s_andn2_b64 vcc, exec, s[70:71]
	v_pk_mul_f32 v[120:121], v[102:103], v[104:105]
	v_pk_mul_f32 v[118:119], v[100:101], v[130:131]
	v_pk_mul_f32 v[122:123], v[96:97], v[130:131]
	s_cbranch_vccnz .LBB0_194
	v_and_b32_e32 v105, 64, v195
	v_xor_b32_e32 v104, 16, v195
	v_add_u32_e32 v105, 64, v105
	v_cmp_lt_i32_e32 vcc, v104, v105
	s_nop 1
	v_cndmask_b32_e32 v104, v195, v104, vcc
	v_lshlrev_b32_e32 v104, 2, v104
	s_waitcnt lgkmcnt(0)
	ds_bpermute_b32 v132, v104, v118
	ds_bpermute_b32 v136, v104, v122
	ds_bpermute_b32 v133, v104, v119
	ds_bpermute_b32 v137, v104, v123
	ds_bpermute_b32 v126, v104, v120
	ds_bpermute_b32 v140, v104, v124
	ds_bpermute_b32 v127, v104, v121
	ds_bpermute_b32 v141, v104, v125
	s_and_saveexec_b64 s[70:71], s[0:1]
	s_cbranch_execz .LBB0_193
	v_lshlrev_b32_e32 v104, 2, v129
	global_load_dwordx4 v[166:169], v104, s[64:65]
	global_load_dwordx4 v[170:173], v104, s[44:45]
	global_load_dwordx4 v[174:177], v104, s[64:65] offset:16
	global_load_dwordx4 v[198:201], v104, s[44:45] offset:16
	s_waitcnt vmcnt(0)
	v_pk_mul_f32 v[104:105], v[120:121], v[168:169]
	v_pk_mul_f32 v[114:115], v[118:119], v[166:167]
	s_waitcnt lgkmcnt(5)
	v_pk_mul_f32 v[134:135], v[170:171], v[132:133]
	s_waitcnt lgkmcnt(1)
	v_pk_mul_f32 v[138:139], v[172:173], v[126:127]
	v_pk_mul_f32 v[126:127], v[124:125], v[176:177]
	v_pk_mul_f32 v[132:133], v[122:123], v[174:175]
	v_pk_mul_f32 v[136:137], v[198:199], v[136:137]
	s_waitcnt lgkmcnt(0)
	v_pk_mul_f32 v[140:141], v[200:201], v[140:141]
	s_and_saveexec_b64 s[78:79], s[4:5]
	s_xor_b64 s[78:79], exec, s[78:79]
	v_pk_add_f32 v[120:121], v[104:105], v[138:139]
	v_pk_add_f32 v[118:119], v[114:115], v[134:135]
	v_pk_add_f32 v[124:125], v[126:127], v[140:141]
	v_pk_add_f32 v[122:123], v[132:133], v[136:137]
	s_andn2_saveexec_b64 s[78:79], s[78:79]
	v_sub_f32_e32 v121, v105, v139
	v_sub_f32_e32 v120, v104, v138
	v_sub_f32_e32 v119, v115, v135
	v_sub_f32_e32 v118, v114, v134
	v_sub_f32_e32 v125, v127, v141
	v_sub_f32_e32 v124, v126, v140
	v_sub_f32_e32 v123, v133, v137
	v_sub_f32_e32 v122, v132, v136
	s_or_b64 exec, exec, s[78:79]

.LBB0_194:
	v_cvt_pk_bf16_f32 v118, v118, v119
	v_cvt_pk_bf16_f32 v119, v120, v121
	v_cvt_pk_bf16_f32 v120, v122, v123
	v_cvt_pk_bf16_f32 v121, v124, v125
	s_mov_b64 s[78:79], 0
	global_store_dwordx4 v[108:109], v[118:121], off offset:256
.LBB0_195:
	s_and_b64 vcc, exec, s[78:79]
	s_cbranch_vccz .LBB0_197
	v_pk_mul_f32 v[100:101], v[100:101], v[130:131]
	v_mov_b32_e32 v104, v130
	v_mov_b32_e32 v105, v130
	v_mul_f32_e32 v100, 0xbfb8aa3b, v100
	v_pk_mul_f32 v[108:109], v[110:111], v[104:105]
	v_exp_f32_e32 v110, v100
	v_mul_f32_e32 v100, 0xbfb8aa3b, v101
	v_exp_f32_e32 v111, v100
	v_pk_mul_f32 v[100:101], v[106:107], v[104:105]
	v_add_f32_e32 v106, 1.0, v110
	v_pk_mul_f32 v[102:103], v[102:103], v[104:105]
	v_add_f32_e32 v107, 1.0, v111
	v_rcp_f32_e32 v106, v106
	v_rcp_f32_e32 v107, v107
	v_mul_f32_e32 v102, 0xbfb8aa3b, v102
	v_exp_f32_e32 v102, v102
	v_mul_f32_e32 v103, 0xbfb8aa3b, v103
	v_exp_f32_e32 v103, v103
	v_pk_mul_f32 v[98:99], v[98:99], v[104:105]
	v_pk_mul_f32 v[104:105], v[96:97], v[130:131]
	v_pk_mul_f32 v[96:97], v[116:117], v[106:107]
	v_mul_f32_e32 v98, 0xbfb8aa3b, v98
	v_cvt_pk_bf16_f32 v96, v96, v97
	v_add_f32_e32 v97, 1.0, v102
	v_rcp_f32_e32 v102, v97
	v_add_f32_e32 v97, 1.0, v103
	v_rcp_f32_e32 v103, v97
	v_mul_f32_e32 v97, 0xbfb8aa3b, v104
	v_exp_f32_e32 v97, v97
	v_mul_f32_e32 v104, 0xbfb8aa3b, v105
	v_exp_f32_e32 v105, v104
	v_exp_f32_e32 v98, v98
	v_mul_f32_e32 v99, 0xbfb8aa3b, v99
	v_exp_f32_e32 v99, v99
	v_add_f32_e32 v97, 1.0, v97
	v_rcp_f32_e32 v104, v97
	v_add_f32_e32 v97, 1.0, v105
	v_rcp_f32_e32 v105, v97
	v_add_f32_e32 v97, 1.0, v98
	v_rcp_f32_e32 v106, v97
	v_add_f32_e32 v97, 1.0, v99
	v_rcp_f32_e32 v107, v97
	v_pk_mul_f32 v[98:99], v[112:113], v[104:105]
	v_ashrrev_i32_e32 v129, 31, v128
	v_cvt_pk_bf16_f32 v98, v98, v99
	v_pk_mul_f32 v[100:101], v[100:101], v[106:107]
	s_lshl_b32 s70, s86, 1
	v_cvt_pk_bf16_f32 v99, v100, v101
	v_lshlrev_b64 v[100:101], 10, v[128:129]
	v_lshl_add_u64 v[100:101], s[42:43], 0, v[100:101]
	v_lshl_add_u64 v[100:101], v[100:101], 0, s[22:23]
	s_mov_b32 s71, s23
	v_pk_mul_f32 v[102:103], v[108:109], v[102:103]
	v_lshl_add_u64 v[100:101], v[100:101], 0, s[70:71]
	v_cvt_pk_bf16_f32 v97, v102, v103
	v_lshl_add_u64 v[100:101], v[100:101], 0, v[152:153]
	global_store_dwordx4 v[100:101], v[96:99], off offset:-768

.LBB0_207:
	v_mov_b64_e32 v[92:93], s[76:77]
	s_or_b32 s37, s22, 0x80
	v_mad_i64_i32 v[92:93], s[70:71], v112, s92, v[92:93]
	s_cmp_lt_i32 s37, s89
	s_cselect_b64 s[70:71], -1, 0
	v_cvt_pk_bf16_f32 v102, v104, v105
	v_cvt_pk_bf16_f32 v103, v106, v107
	v_cvt_pk_bf16_f32 v104, v108, v109
	v_cvt_pk_bf16_f32 v105, v110, v111
	v_lshl_add_u64 v[92:93], v[164:165], 1, v[92:93]
	s_and_b64 s[70:71], s[30:31], s[70:71]
	global_store_dwordx4 v[92:93], v[102:105], off
	v_pk_mul_f32 v[108:109], v[82:83], v[88:89]
	s_andn2_b64 vcc, exec, s[70:71]
	v_pk_mul_f32 v[104:105], v[86:87], v[88:89]
	v_pk_mul_f32 v[102:103], v[84:85], v[114:115]
	v_pk_mul_f32 v[106:107], v[80:81], v[114:115]
	s_cbranch_vccnz .LBB0_215
	v_and_b32_e32 v89, 64, v195
	v_xor_b32_e32 v88, 16, v195
	v_add_u32_e32 v89, 64, v89
	v_cmp_lt_i32_e32 vcc, v88, v89
	s_nop 1
	v_cndmask_b32_e32 v88, v195, v88, vcc
	v_lshlrev_b32_e32 v88, 2, v88
	s_waitcnt lgkmcnt(0)
	ds_bpermute_b32 v116, v88, v102
	ds_bpermute_b32 v120, v88, v106
	ds_bpermute_b32 v117, v88, v103
	ds_bpermute_b32 v121, v88, v107
	ds_bpermute_b32 v110, v88, v104
	ds_bpermute_b32 v124, v88, v108
	ds_bpermute_b32 v111, v88, v105
	ds_bpermute_b32 v125, v88, v109
	s_and_saveexec_b64 s[70:71], s[0:1]
	s_cbranch_execz .LBB0_214
	v_lshlrev_b32_e32 v88, 2, v113
	global_load_dwordx4 v[126:129], v88, s[64:65]
	global_load_dwordx4 v[130:133], v88, s[44:45]
	global_load_dwordx4 v[134:137], v88, s[64:65] offset:16
	global_load_dwordx4 v[138:141], v88, s[44:45] offset:16
	s_waitcnt vmcnt(0)
	v_pk_mul_f32 v[88:89], v[104:105], v[128:129]
	v_pk_mul_f32 v[98:99], v[102:103], v[126:127]
	s_waitcnt lgkmcnt(5)
	v_pk_mul_f32 v[118:119], v[130:131], v[116:117]
	s_waitcnt lgkmcnt(1)
	v_pk_mul_f32 v[122:123], v[132:133], v[110:111]
	v_pk_mul_f32 v[110:111], v[108:109], v[136:137]
	v_pk_mul_f32 v[116:117], v[106:107], v[134:135]
	v_pk_mul_f32 v[120:121], v[138:139], v[120:121]
	s_waitcnt lgkmcnt(0)
	v_pk_mul_f32 v[124:125], v[140:141], v[124:125]
	s_and_saveexec_b64 s[78:79], s[4:5]
	s_xor_b64 s[78:79], exec, s[78:79]
	v_pk_add_f32 v[104:105], v[88:89], v[122:123]
	v_pk_add_f32 v[102:103], v[98:99], v[118:119]
	v_pk_add_f32 v[108:109], v[110:111], v[124:125]
	v_pk_add_f32 v[106:107], v[116:117], v[120:121]
	s_andn2_saveexec_b64 s[78:79], s[78:79]
	v_sub_f32_e32 v105, v89, v123
	v_sub_f32_e32 v104, v88, v122
	v_sub_f32_e32 v103, v99, v119
	v_sub_f32_e32 v102, v98, v118
	v_sub_f32_e32 v109, v111, v125
	v_sub_f32_e32 v108, v110, v124
	v_sub_f32_e32 v107, v117, v121
	v_sub_f32_e32 v106, v116, v120
	s_or_b64 exec, exec, s[78:79]

.LBB0_215:
	v_cvt_pk_bf16_f32 v102, v102, v103
	v_cvt_pk_bf16_f32 v103, v104, v105
	v_cvt_pk_bf16_f32 v104, v106, v107
	v_cvt_pk_bf16_f32 v105, v108, v109
	s_mov_b64 s[70:71], 0
	global_store_dwordx4 v[92:93], v[102:105], off offset:256
.LBB0_216:
	s_and_b64 vcc, exec, s[70:71]
	s_cbranch_vccz .LBB0_218
	v_pk_mul_f32 v[84:85], v[84:85], v[114:115]
	v_mov_b32_e32 v88, v114
	v_mov_b32_e32 v89, v114
	v_mul_f32_e32 v84, 0xbfb8aa3b, v84
	v_pk_mul_f32 v[92:93], v[94:95], v[88:89]
	v_exp_f32_e32 v94, v84
	v_mul_f32_e32 v84, 0xbfb8aa3b, v85
	v_exp_f32_e32 v95, v84
	v_pk_mul_f32 v[84:85], v[90:91], v[88:89]
	v_add_f32_e32 v90, 1.0, v94
	v_pk_mul_f32 v[86:87], v[86:87], v[88:89]
	v_add_f32_e32 v91, 1.0, v95
	v_rcp_f32_e32 v90, v90
	v_rcp_f32_e32 v91, v91
	v_mul_f32_e32 v86, 0xbfb8aa3b, v86
	v_exp_f32_e32 v86, v86
	v_mul_f32_e32 v87, 0xbfb8aa3b, v87
	v_exp_f32_e32 v87, v87
	v_pk_mul_f32 v[82:83], v[82:83], v[88:89]
	v_pk_mul_f32 v[88:89], v[80:81], v[114:115]
	v_pk_mul_f32 v[80:81], v[100:101], v[90:91]
	v_mul_f32_e32 v82, 0xbfb8aa3b, v82
	v_cvt_pk_bf16_f32 v80, v80, v81
	v_add_f32_e32 v81, 1.0, v86
	v_rcp_f32_e32 v86, v81
	v_add_f32_e32 v81, 1.0, v87
	v_rcp_f32_e32 v87, v81
	v_mul_f32_e32 v81, 0xbfb8aa3b, v88
	v_exp_f32_e32 v81, v81
	v_mul_f32_e32 v88, 0xbfb8aa3b, v89
	v_exp_f32_e32 v89, v88
	v_exp_f32_e32 v82, v82
	v_mul_f32_e32 v83, 0xbfb8aa3b, v83
	v_exp_f32_e32 v83, v83
	v_add_f32_e32 v81, 1.0, v81
	v_rcp_f32_e32 v88, v81
	v_add_f32_e32 v81, 1.0, v89
	v_rcp_f32_e32 v89, v81
	v_add_f32_e32 v81, 1.0, v82
	v_rcp_f32_e32 v90, v81
	v_add_f32_e32 v81, 1.0, v83
	v_rcp_f32_e32 v91, v81
	v_pk_mul_f32 v[82:83], v[96:97], v[88:89]
	v_ashrrev_i32_e32 v113, 31, v112
	v_cvt_pk_bf16_f32 v82, v82, v83
	v_pk_mul_f32 v[84:85], v[84:85], v[90:91]
	s_lshl_b32 s70, s86, 1
	v_cvt_pk_bf16_f32 v83, v84, v85
	v_lshlrev_b64 v[84:85], 10, v[112:113]
	v_lshl_add_u64 v[84:85], s[42:43], 0, v[84:85]
	v_lshl_add_u64 v[84:85], v[84:85], 0, s[22:23]
	s_mov_b32 s71, s23
	v_pk_mul_f32 v[86:87], v[92:93], v[86:87]
	v_lshl_add_u64 v[84:85], v[84:85], 0, s[70:71]
	v_cvt_pk_bf16_f32 v81, v86, v87
	v_lshl_add_u64 v[84:85], v[84:85], 0, v[152:153]
	global_store_dwordx4 v[84:85], v[80:83], off offset:-768

.LBB0_228:
	v_mov_b64_e32 v[76:77], s[76:77]
	s_or_b32 s37, s22, 0x80
	v_mad_i64_i32 v[76:77], s[70:71], v96, s92, v[76:77]
	s_cmp_lt_i32 s37, s89
	s_cselect_b64 s[70:71], -1, 0
	v_cvt_pk_bf16_f32 v86, v88, v89
	v_cvt_pk_bf16_f32 v87, v90, v91
	v_cvt_pk_bf16_f32 v88, v92, v93
	v_cvt_pk_bf16_f32 v89, v94, v95
	v_lshl_add_u64 v[76:77], v[164:165], 1, v[76:77]
	s_and_b64 s[70:71], s[30:31], s[70:71]
	global_store_dwordx4 v[76:77], v[86:89], off
	v_pk_mul_f32 v[92:93], v[66:67], v[72:73]
	s_andn2_b64 vcc, exec, s[70:71]
	v_pk_mul_f32 v[88:89], v[70:71], v[72:73]
	v_pk_mul_f32 v[86:87], v[68:69], v[98:99]
	v_pk_mul_f32 v[90:91], v[64:65], v[98:99]
	s_cbranch_vccnz .LBB0_236
	v_and_b32_e32 v73, 64, v195
	v_xor_b32_e32 v72, 16, v195
	v_add_u32_e32 v73, 64, v73
	v_cmp_lt_i32_e32 vcc, v72, v73
	s_nop 1
	v_cndmask_b32_e32 v72, v195, v72, vcc
	v_lshlrev_b32_e32 v72, 2, v72
	s_waitcnt lgkmcnt(0)
	ds_bpermute_b32 v100, v72, v86
	ds_bpermute_b32 v104, v72, v90
	ds_bpermute_b32 v101, v72, v87
	ds_bpermute_b32 v105, v72, v91
	ds_bpermute_b32 v94, v72, v88
	ds_bpermute_b32 v108, v72, v92
	ds_bpermute_b32 v95, v72, v89
	ds_bpermute_b32 v109, v72, v93
	s_and_saveexec_b64 s[70:71], s[0:1]
	s_cbranch_execz .LBB0_235
	v_lshlrev_b32_e32 v72, 2, v97
	global_load_dwordx4 v[110:113], v72, s[64:65]
	global_load_dwordx4 v[114:117], v72, s[44:45]
	global_load_dwordx4 v[118:121], v72, s[64:65] offset:16
	global_load_dwordx4 v[122:125], v72, s[44:45] offset:16
	s_waitcnt vmcnt(0)
	v_pk_mul_f32 v[72:73], v[88:89], v[112:113]
	v_pk_mul_f32 v[82:83], v[86:87], v[110:111]
	s_waitcnt lgkmcnt(5)
	v_pk_mul_f32 v[102:103], v[114:115], v[100:101]
	s_waitcnt lgkmcnt(1)
	v_pk_mul_f32 v[106:107], v[116:117], v[94:95]
	v_pk_mul_f32 v[94:95], v[92:93], v[120:121]
	v_pk_mul_f32 v[100:101], v[90:91], v[118:119]
	v_pk_mul_f32 v[104:105], v[122:123], v[104:105]
	s_waitcnt lgkmcnt(0)
	v_pk_mul_f32 v[108:109], v[124:125], v[108:109]
	s_and_saveexec_b64 s[78:79], s[4:5]
	s_xor_b64 s[78:79], exec, s[78:79]
	v_pk_add_f32 v[88:89], v[72:73], v[106:107]
	v_pk_add_f32 v[86:87], v[82:83], v[102:103]
	v_pk_add_f32 v[92:93], v[94:95], v[108:109]
	v_pk_add_f32 v[90:91], v[100:101], v[104:105]
	s_andn2_saveexec_b64 s[78:79], s[78:79]
	v_sub_f32_e32 v89, v73, v107
	v_sub_f32_e32 v88, v72, v106
	v_sub_f32_e32 v87, v83, v103
	v_sub_f32_e32 v86, v82, v102
	v_sub_f32_e32 v93, v95, v109
	v_sub_f32_e32 v92, v94, v108
	v_sub_f32_e32 v91, v101, v105
	v_sub_f32_e32 v90, v100, v104
	s_or_b64 exec, exec, s[78:79]

.LBB0_236:
	v_cvt_pk_bf16_f32 v86, v86, v87
	v_cvt_pk_bf16_f32 v87, v88, v89
	v_cvt_pk_bf16_f32 v88, v90, v91
	v_cvt_pk_bf16_f32 v89, v92, v93
	s_mov_b64 s[70:71], 0
	global_store_dwordx4 v[76:77], v[86:89], off offset:256
.LBB0_237:
	s_and_b64 vcc, exec, s[70:71]
	s_cbranch_vccz .LBB0_239
	v_pk_mul_f32 v[68:69], v[68:69], v[98:99]
	v_mov_b32_e32 v72, v98
	v_mov_b32_e32 v73, v98
	v_mul_f32_e32 v68, 0xbfb8aa3b, v68
	v_pk_mul_f32 v[76:77], v[78:79], v[72:73]
	v_exp_f32_e32 v78, v68
	v_mul_f32_e32 v68, 0xbfb8aa3b, v69
	v_exp_f32_e32 v79, v68
	v_pk_mul_f32 v[68:69], v[74:75], v[72:73]
	v_add_f32_e32 v74, 1.0, v78
	v_pk_mul_f32 v[70:71], v[70:71], v[72:73]
	v_add_f32_e32 v75, 1.0, v79
	v_rcp_f32_e32 v74, v74
	v_rcp_f32_e32 v75, v75
	v_mul_f32_e32 v70, 0xbfb8aa3b, v70
	v_exp_f32_e32 v70, v70
	v_mul_f32_e32 v71, 0xbfb8aa3b, v71
	v_exp_f32_e32 v71, v71
	v_pk_mul_f32 v[66:67], v[66:67], v[72:73]
	v_pk_mul_f32 v[72:73], v[64:65], v[98:99]
	v_pk_mul_f32 v[64:65], v[84:85], v[74:75]
	v_mul_f32_e32 v66, 0xbfb8aa3b, v66
	v_cvt_pk_bf16_f32 v64, v64, v65
	v_add_f32_e32 v65, 1.0, v70
	v_rcp_f32_e32 v70, v65
	v_add_f32_e32 v65, 1.0, v71
	v_rcp_f32_e32 v71, v65
	v_mul_f32_e32 v65, 0xbfb8aa3b, v72
	v_exp_f32_e32 v65, v65
	v_mul_f32_e32 v72, 0xbfb8aa3b, v73
	v_exp_f32_e32 v73, v72
	v_exp_f32_e32 v66, v66
	v_mul_f32_e32 v67, 0xbfb8aa3b, v67
	v_exp_f32_e32 v67, v67
	v_add_f32_e32 v65, 1.0, v65
	v_rcp_f32_e32 v72, v65
	v_add_f32_e32 v65, 1.0, v73
	v_rcp_f32_e32 v73, v65
	v_add_f32_e32 v65, 1.0, v66
	v_rcp_f32_e32 v74, v65
	v_add_f32_e32 v65, 1.0, v67
	v_rcp_f32_e32 v75, v65
	v_pk_mul_f32 v[66:67], v[80:81], v[72:73]
	v_ashrrev_i32_e32 v97, 31, v96
	v_cvt_pk_bf16_f32 v66, v66, v67
	v_pk_mul_f32 v[68:69], v[68:69], v[74:75]
	s_lshl_b32 s70, s86, 1
	v_cvt_pk_bf16_f32 v67, v68, v69
	v_lshlrev_b64 v[68:69], 10, v[96:97]
	v_lshl_add_u64 v[68:69], s[42:43], 0, v[68:69]
	v_lshl_add_u64 v[68:69], v[68:69], 0, s[22:23]
	s_mov_b32 s71, s23
	v_pk_mul_f32 v[70:71], v[76:77], v[70:71]
	v_lshl_add_u64 v[68:69], v[68:69], 0, s[70:71]
	v_cvt_pk_bf16_f32 v65, v70, v71
	v_lshl_add_u64 v[68:69], v[68:69], 0, v[152:153]
	global_store_dwordx4 v[68:69], v[64:67], off offset:-768

.LBB0_249:
	v_mov_b64_e32 v[60:61], s[76:77]
	s_or_b32 s37, s22, 0x80
	v_mad_i64_i32 v[60:61], s[70:71], v80, s92, v[60:61]
	s_cmp_lt_i32 s37, s89
	s_cselect_b64 s[70:71], -1, 0
	v_cvt_pk_bf16_f32 v70, v72, v73
	v_cvt_pk_bf16_f32 v71, v74, v75
	v_cvt_pk_bf16_f32 v72, v76, v77
	v_cvt_pk_bf16_f32 v73, v78, v79
	v_lshl_add_u64 v[60:61], v[164:165], 1, v[60:61]
	s_and_b64 s[70:71], s[30:31], s[70:71]
	global_store_dwordx4 v[60:61], v[70:73], off
	v_pk_mul_f32 v[76:77], v[50:51], v[56:57]
	s_andn2_b64 vcc, exec, s[70:71]
	v_pk_mul_f32 v[72:73], v[54:55], v[56:57]
	v_pk_mul_f32 v[70:71], v[52:53], v[82:83]
	v_pk_mul_f32 v[74:75], v[48:49], v[82:83]
	s_cbranch_vccnz .LBB0_257
	v_and_b32_e32 v57, 64, v195
	v_xor_b32_e32 v56, 16, v195
	v_add_u32_e32 v57, 64, v57
	v_cmp_lt_i32_e32 vcc, v56, v57
	s_nop 1
	v_cndmask_b32_e32 v56, v195, v56, vcc
	v_lshlrev_b32_e32 v56, 2, v56
	s_waitcnt lgkmcnt(0)
	ds_bpermute_b32 v84, v56, v70
	ds_bpermute_b32 v88, v56, v74
	ds_bpermute_b32 v85, v56, v71
	ds_bpermute_b32 v89, v56, v75
	ds_bpermute_b32 v78, v56, v72
	ds_bpermute_b32 v92, v56, v76
	ds_bpermute_b32 v79, v56, v73
	ds_bpermute_b32 v93, v56, v77
	s_and_saveexec_b64 s[70:71], s[0:1]
	s_cbranch_execz .LBB0_256
	v_lshlrev_b32_e32 v56, 2, v81
	global_load_dwordx4 v[94:97], v56, s[64:65]
	global_load_dwordx4 v[98:101], v56, s[44:45]
	global_load_dwordx4 v[102:105], v56, s[64:65] offset:16
	global_load_dwordx4 v[106:109], v56, s[44:45] offset:16
	s_waitcnt vmcnt(0)
	v_pk_mul_f32 v[56:57], v[72:73], v[96:97]
	v_pk_mul_f32 v[66:67], v[70:71], v[94:95]
	s_waitcnt lgkmcnt(5)
	v_pk_mul_f32 v[86:87], v[98:99], v[84:85]
	s_waitcnt lgkmcnt(1)
	v_pk_mul_f32 v[90:91], v[100:101], v[78:79]
	v_pk_mul_f32 v[78:79], v[76:77], v[104:105]
	v_pk_mul_f32 v[84:85], v[74:75], v[102:103]
	v_pk_mul_f32 v[88:89], v[106:107], v[88:89]
	s_waitcnt lgkmcnt(0)
	v_pk_mul_f32 v[92:93], v[108:109], v[92:93]
	s_and_saveexec_b64 s[78:79], s[4:5]
	s_xor_b64 s[78:79], exec, s[78:79]
	v_pk_add_f32 v[72:73], v[56:57], v[90:91]
	v_pk_add_f32 v[70:71], v[66:67], v[86:87]
	v_pk_add_f32 v[76:77], v[78:79], v[92:93]
	v_pk_add_f32 v[74:75], v[84:85], v[88:89]
	s_andn2_saveexec_b64 s[78:79], s[78:79]
	v_sub_f32_e32 v73, v57, v91
	v_sub_f32_e32 v72, v56, v90
	v_sub_f32_e32 v71, v67, v87
	v_sub_f32_e32 v70, v66, v86
	v_sub_f32_e32 v77, v79, v93
	v_sub_f32_e32 v76, v78, v92
	v_sub_f32_e32 v75, v85, v89
	v_sub_f32_e32 v74, v84, v88
	s_or_b64 exec, exec, s[78:79]

.LBB0_257:
	v_cvt_pk_bf16_f32 v70, v70, v71
	v_cvt_pk_bf16_f32 v71, v72, v73
	v_cvt_pk_bf16_f32 v72, v74, v75
	v_cvt_pk_bf16_f32 v73, v76, v77
	s_mov_b64 s[70:71], 0
	global_store_dwordx4 v[60:61], v[70:73], off offset:256
.LBB0_258:
	s_and_b64 vcc, exec, s[70:71]
	s_cbranch_vccz .LBB0_260
	v_pk_mul_f32 v[52:53], v[52:53], v[82:83]
	v_mov_b32_e32 v56, v82
	v_mov_b32_e32 v57, v82
	v_mul_f32_e32 v52, 0xbfb8aa3b, v52
	v_pk_mul_f32 v[60:61], v[62:63], v[56:57]
	v_exp_f32_e32 v62, v52
	v_mul_f32_e32 v52, 0xbfb8aa3b, v53
	v_exp_f32_e32 v63, v52
	v_pk_mul_f32 v[52:53], v[58:59], v[56:57]
	v_add_f32_e32 v58, 1.0, v62
	v_pk_mul_f32 v[54:55], v[54:55], v[56:57]
	v_add_f32_e32 v59, 1.0, v63
	v_rcp_f32_e32 v58, v58
	v_rcp_f32_e32 v59, v59
	v_mul_f32_e32 v54, 0xbfb8aa3b, v54
	v_exp_f32_e32 v54, v54
	v_mul_f32_e32 v55, 0xbfb8aa3b, v55
	v_exp_f32_e32 v55, v55
	v_pk_mul_f32 v[50:51], v[50:51], v[56:57]
	v_pk_mul_f32 v[56:57], v[48:49], v[82:83]
	v_pk_mul_f32 v[48:49], v[68:69], v[58:59]
	v_mul_f32_e32 v50, 0xbfb8aa3b, v50
	v_cvt_pk_bf16_f32 v48, v48, v49
	v_add_f32_e32 v49, 1.0, v54
	v_rcp_f32_e32 v54, v49
	v_add_f32_e32 v49, 1.0, v55
	v_rcp_f32_e32 v55, v49
	v_mul_f32_e32 v49, 0xbfb8aa3b, v56
	v_exp_f32_e32 v49, v49
	v_mul_f32_e32 v56, 0xbfb8aa3b, v57
	v_exp_f32_e32 v57, v56
	v_exp_f32_e32 v50, v50
	v_mul_f32_e32 v51, 0xbfb8aa3b, v51
	v_exp_f32_e32 v51, v51
	v_add_f32_e32 v49, 1.0, v49
	v_rcp_f32_e32 v56, v49
	v_add_f32_e32 v49, 1.0, v57
	v_rcp_f32_e32 v57, v49
	v_add_f32_e32 v49, 1.0, v50
	v_rcp_f32_e32 v58, v49
	v_add_f32_e32 v49, 1.0, v51
	v_rcp_f32_e32 v59, v49
	v_pk_mul_f32 v[50:51], v[64:65], v[56:57]
	v_ashrrev_i32_e32 v81, 31, v80
	v_cvt_pk_bf16_f32 v50, v50, v51
	v_pk_mul_f32 v[52:53], v[52:53], v[58:59]
	s_lshl_b32 s70, s86, 1
	v_cvt_pk_bf16_f32 v51, v52, v53
	v_lshlrev_b64 v[52:53], 10, v[80:81]
	v_lshl_add_u64 v[52:53], s[42:43], 0, v[52:53]
	v_lshl_add_u64 v[52:53], v[52:53], 0, s[22:23]
	s_mov_b32 s71, s23
	v_pk_mul_f32 v[54:55], v[60:61], v[54:55]
	v_lshl_add_u64 v[52:53], v[52:53], 0, s[70:71]
	v_cvt_pk_bf16_f32 v49, v54, v55
	v_lshl_add_u64 v[52:53], v[52:53], 0, v[152:153]
	global_store_dwordx4 v[52:53], v[48:51], off offset:-768

.LBB0_270:
	v_mov_b64_e32 v[44:45], s[76:77]
	s_or_b32 s37, s22, 0x80
	v_mad_i64_i32 v[44:45], s[70:71], v64, s92, v[44:45]
	s_cmp_lt_i32 s37, s89
	s_cselect_b64 s[70:71], -1, 0
	v_cvt_pk_bf16_f32 v54, v56, v57
	v_cvt_pk_bf16_f32 v55, v58, v59
	v_cvt_pk_bf16_f32 v56, v60, v61
	v_cvt_pk_bf16_f32 v57, v62, v63
	v_lshl_add_u64 v[44:45], v[164:165], 1, v[44:45]
	s_and_b64 s[70:71], s[30:31], s[70:71]
	global_store_dwordx4 v[44:45], v[54:57], off
	v_pk_mul_f32 v[60:61], v[34:35], v[40:41]
	s_andn2_b64 vcc, exec, s[70:71]
	v_pk_mul_f32 v[56:57], v[38:39], v[40:41]
	v_pk_mul_f32 v[54:55], v[36:37], v[66:67]
	v_pk_mul_f32 v[58:59], v[32:33], v[66:67]
	s_cbranch_vccnz .LBB0_278
	v_and_b32_e32 v41, 64, v195
	v_xor_b32_e32 v40, 16, v195
	v_add_u32_e32 v41, 64, v41
	v_cmp_lt_i32_e32 vcc, v40, v41
	s_nop 1
	v_cndmask_b32_e32 v40, v195, v40, vcc
	v_lshlrev_b32_e32 v40, 2, v40
	s_waitcnt lgkmcnt(0)
	ds_bpermute_b32 v68, v40, v54
	ds_bpermute_b32 v72, v40, v58
	ds_bpermute_b32 v69, v40, v55
	ds_bpermute_b32 v73, v40, v59
	ds_bpermute_b32 v62, v40, v56
	ds_bpermute_b32 v76, v40, v60
	ds_bpermute_b32 v63, v40, v57
	ds_bpermute_b32 v77, v40, v61
	s_and_saveexec_b64 s[70:71], s[0:1]
	s_cbranch_execz .LBB0_277
	v_lshlrev_b32_e32 v40, 2, v65
	global_load_dwordx4 v[78:81], v40, s[64:65]
	global_load_dwordx4 v[82:85], v40, s[44:45]
	global_load_dwordx4 v[86:89], v40, s[64:65] offset:16
	global_load_dwordx4 v[90:93], v40, s[44:45] offset:16
	s_waitcnt vmcnt(0)
	v_pk_mul_f32 v[40:41], v[56:57], v[80:81]
	v_pk_mul_f32 v[50:51], v[54:55], v[78:79]
	s_waitcnt lgkmcnt(5)
	v_pk_mul_f32 v[70:71], v[82:83], v[68:69]
	s_waitcnt lgkmcnt(1)
	v_pk_mul_f32 v[74:75], v[84:85], v[62:63]
	v_pk_mul_f32 v[62:63], v[60:61], v[88:89]
	v_pk_mul_f32 v[68:69], v[58:59], v[86:87]
	v_pk_mul_f32 v[72:73], v[90:91], v[72:73]
	s_waitcnt lgkmcnt(0)
	v_pk_mul_f32 v[76:77], v[92:93], v[76:77]
	s_and_saveexec_b64 s[78:79], s[4:5]
	s_xor_b64 s[78:79], exec, s[78:79]
	v_pk_add_f32 v[56:57], v[40:41], v[74:75]
	v_pk_add_f32 v[54:55], v[50:51], v[70:71]
	v_pk_add_f32 v[60:61], v[62:63], v[76:77]
	v_pk_add_f32 v[58:59], v[68:69], v[72:73]
	s_andn2_saveexec_b64 s[78:79], s[78:79]
	v_sub_f32_e32 v57, v41, v75
	v_sub_f32_e32 v56, v40, v74
	v_sub_f32_e32 v55, v51, v71
	v_sub_f32_e32 v54, v50, v70
	v_sub_f32_e32 v61, v63, v77
	v_sub_f32_e32 v60, v62, v76
	v_sub_f32_e32 v59, v69, v73
	v_sub_f32_e32 v58, v68, v72
	s_or_b64 exec, exec, s[78:79]

.LBB0_278:
	v_cvt_pk_bf16_f32 v54, v54, v55
	v_cvt_pk_bf16_f32 v55, v56, v57
	v_cvt_pk_bf16_f32 v56, v58, v59
	v_cvt_pk_bf16_f32 v57, v60, v61
	s_mov_b64 s[70:71], 0
	global_store_dwordx4 v[44:45], v[54:57], off offset:256
.LBB0_279:
	s_and_b64 vcc, exec, s[70:71]
	s_cbranch_vccz .LBB0_281
	v_pk_mul_f32 v[36:37], v[36:37], v[66:67]
	v_mov_b32_e32 v40, v66
	v_mov_b32_e32 v41, v66
	v_mul_f32_e32 v36, 0xbfb8aa3b, v36
	v_pk_mul_f32 v[44:45], v[46:47], v[40:41]
	v_exp_f32_e32 v46, v36
	v_mul_f32_e32 v36, 0xbfb8aa3b, v37
	v_exp_f32_e32 v47, v36
	v_pk_mul_f32 v[36:37], v[42:43], v[40:41]
	v_add_f32_e32 v42, 1.0, v46
	v_pk_mul_f32 v[38:39], v[38:39], v[40:41]
	v_add_f32_e32 v43, 1.0, v47
	v_rcp_f32_e32 v42, v42
	v_rcp_f32_e32 v43, v43
	v_mul_f32_e32 v38, 0xbfb8aa3b, v38
	v_exp_f32_e32 v38, v38
	v_mul_f32_e32 v39, 0xbfb8aa3b, v39
	v_exp_f32_e32 v39, v39
	v_pk_mul_f32 v[34:35], v[34:35], v[40:41]
	v_pk_mul_f32 v[40:41], v[32:33], v[66:67]
	v_pk_mul_f32 v[32:33], v[52:53], v[42:43]
	v_mul_f32_e32 v34, 0xbfb8aa3b, v34
	v_cvt_pk_bf16_f32 v32, v32, v33
	v_add_f32_e32 v33, 1.0, v38
	v_rcp_f32_e32 v38, v33
	v_add_f32_e32 v33, 1.0, v39
	v_rcp_f32_e32 v39, v33
	v_mul_f32_e32 v33, 0xbfb8aa3b, v40
	v_exp_f32_e32 v33, v33
	v_mul_f32_e32 v40, 0xbfb8aa3b, v41
	v_exp_f32_e32 v41, v40
	v_exp_f32_e32 v34, v34
	v_mul_f32_e32 v35, 0xbfb8aa3b, v35
	v_exp_f32_e32 v35, v35
	v_add_f32_e32 v33, 1.0, v33
	v_rcp_f32_e32 v40, v33
	v_add_f32_e32 v33, 1.0, v41
	v_rcp_f32_e32 v41, v33
	v_add_f32_e32 v33, 1.0, v34
	v_rcp_f32_e32 v42, v33
	v_add_f32_e32 v33, 1.0, v35
	v_rcp_f32_e32 v43, v33
	v_pk_mul_f32 v[34:35], v[48:49], v[40:41]
	v_ashrrev_i32_e32 v65, 31, v64
	v_cvt_pk_bf16_f32 v34, v34, v35
	v_pk_mul_f32 v[36:37], v[36:37], v[42:43]
	s_lshl_b32 s70, s86, 1
	v_cvt_pk_bf16_f32 v35, v36, v37
	v_lshlrev_b64 v[36:37], 10, v[64:65]
	v_lshl_add_u64 v[36:37], s[42:43], 0, v[36:37]
	v_lshl_add_u64 v[36:37], v[36:37], 0, s[22:23]
	s_mov_b32 s71, s23
	v_pk_mul_f32 v[38:39], v[44:45], v[38:39]
	v_lshl_add_u64 v[36:37], v[36:37], 0, s[70:71]
	v_cvt_pk_bf16_f32 v33, v38, v39
	v_lshl_add_u64 v[36:37], v[36:37], 0, v[152:153]
	global_store_dwordx4 v[36:37], v[32:35], off offset:-768

.LBB0_291:
	v_mov_b64_e32 v[28:29], s[76:77]
	s_or_b32 s37, s22, 0x80
	v_mad_i64_i32 v[28:29], s[70:71], v48, s92, v[28:29]
	s_cmp_lt_i32 s37, s89
	s_cselect_b64 s[70:71], -1, 0
	v_cvt_pk_bf16_f32 v38, v40, v41
	v_cvt_pk_bf16_f32 v39, v42, v43
	v_cvt_pk_bf16_f32 v40, v44, v45
	v_cvt_pk_bf16_f32 v41, v46, v47
	v_lshl_add_u64 v[28:29], v[164:165], 1, v[28:29]
	s_and_b64 s[70:71], s[30:31], s[70:71]
	global_store_dwordx4 v[28:29], v[38:41], off
	v_pk_mul_f32 v[44:45], v[18:19], v[24:25]
	s_andn2_b64 vcc, exec, s[70:71]
	v_pk_mul_f32 v[40:41], v[22:23], v[24:25]
	v_pk_mul_f32 v[38:39], v[20:21], v[50:51]
	v_pk_mul_f32 v[42:43], v[16:17], v[50:51]
	s_cbranch_vccnz .LBB0_299
	v_and_b32_e32 v25, 64, v195
	v_xor_b32_e32 v24, 16, v195
	v_add_u32_e32 v25, 64, v25
	v_cmp_lt_i32_e32 vcc, v24, v25
	s_nop 1
	v_cndmask_b32_e32 v24, v195, v24, vcc
	v_lshlrev_b32_e32 v24, 2, v24
	s_waitcnt lgkmcnt(0)
	ds_bpermute_b32 v52, v24, v38
	ds_bpermute_b32 v56, v24, v42
	ds_bpermute_b32 v53, v24, v39
	ds_bpermute_b32 v57, v24, v43
	ds_bpermute_b32 v46, v24, v40
	ds_bpermute_b32 v60, v24, v44
	ds_bpermute_b32 v47, v24, v41
	ds_bpermute_b32 v61, v24, v45
	s_and_saveexec_b64 s[70:71], s[0:1]
	s_cbranch_execz .LBB0_298
	v_lshlrev_b32_e32 v24, 2, v49
	global_load_dwordx4 v[62:65], v24, s[64:65]
	global_load_dwordx4 v[66:69], v24, s[44:45]
	global_load_dwordx4 v[70:73], v24, s[64:65] offset:16
	global_load_dwordx4 v[74:77], v24, s[44:45] offset:16
	s_waitcnt vmcnt(0)
	v_pk_mul_f32 v[24:25], v[40:41], v[64:65]
	v_pk_mul_f32 v[34:35], v[38:39], v[62:63]
	s_waitcnt lgkmcnt(5)
	v_pk_mul_f32 v[54:55], v[66:67], v[52:53]
	s_waitcnt lgkmcnt(1)
	v_pk_mul_f32 v[58:59], v[68:69], v[46:47]
	v_pk_mul_f32 v[46:47], v[44:45], v[72:73]
	v_pk_mul_f32 v[52:53], v[42:43], v[70:71]
	v_pk_mul_f32 v[56:57], v[74:75], v[56:57]
	s_waitcnt lgkmcnt(0)
	v_pk_mul_f32 v[60:61], v[76:77], v[60:61]
	s_and_saveexec_b64 s[78:79], s[4:5]
	s_xor_b64 s[78:79], exec, s[78:79]
	v_pk_add_f32 v[40:41], v[24:25], v[58:59]
	v_pk_add_f32 v[38:39], v[34:35], v[54:55]
	v_pk_add_f32 v[44:45], v[46:47], v[60:61]
	v_pk_add_f32 v[42:43], v[52:53], v[56:57]
	s_andn2_saveexec_b64 s[78:79], s[78:79]
	v_sub_f32_e32 v41, v25, v59
	v_sub_f32_e32 v40, v24, v58
	v_sub_f32_e32 v39, v35, v55
	v_sub_f32_e32 v38, v34, v54
	v_sub_f32_e32 v45, v47, v61
	v_sub_f32_e32 v44, v46, v60
	v_sub_f32_e32 v43, v53, v57
	v_sub_f32_e32 v42, v52, v56
	s_or_b64 exec, exec, s[78:79]

.LBB0_299:
	v_cvt_pk_bf16_f32 v38, v38, v39
	v_cvt_pk_bf16_f32 v39, v40, v41
	v_cvt_pk_bf16_f32 v40, v42, v43
	v_cvt_pk_bf16_f32 v41, v44, v45
	s_mov_b64 s[70:71], 0
	global_store_dwordx4 v[28:29], v[38:41], off offset:256
.LBB0_300:
	s_and_b64 vcc, exec, s[70:71]
	s_cbranch_vccz .LBB0_302
	v_pk_mul_f32 v[20:21], v[20:21], v[50:51]
	v_mov_b32_e32 v24, v50
	v_mov_b32_e32 v25, v50
	v_mul_f32_e32 v20, 0xbfb8aa3b, v20
	v_pk_mul_f32 v[28:29], v[30:31], v[24:25]
	v_exp_f32_e32 v30, v20
	v_mul_f32_e32 v20, 0xbfb8aa3b, v21
	v_exp_f32_e32 v31, v20
	v_pk_mul_f32 v[20:21], v[26:27], v[24:25]
	v_add_f32_e32 v26, 1.0, v30
	v_pk_mul_f32 v[22:23], v[22:23], v[24:25]
	v_add_f32_e32 v27, 1.0, v31
	v_rcp_f32_e32 v26, v26
	v_rcp_f32_e32 v27, v27
	v_mul_f32_e32 v22, 0xbfb8aa3b, v22
	v_exp_f32_e32 v22, v22
	v_mul_f32_e32 v23, 0xbfb8aa3b, v23
	v_exp_f32_e32 v23, v23
	v_pk_mul_f32 v[18:19], v[18:19], v[24:25]
	v_pk_mul_f32 v[24:25], v[16:17], v[50:51]
	v_pk_mul_f32 v[16:17], v[36:37], v[26:27]
	v_mul_f32_e32 v18, 0xbfb8aa3b, v18
	v_cvt_pk_bf16_f32 v16, v16, v17
	v_add_f32_e32 v17, 1.0, v22
	v_rcp_f32_e32 v22, v17
	v_add_f32_e32 v17, 1.0, v23
	v_rcp_f32_e32 v23, v17
	v_mul_f32_e32 v17, 0xbfb8aa3b, v24
	v_exp_f32_e32 v17, v17
	v_mul_f32_e32 v24, 0xbfb8aa3b, v25
	v_exp_f32_e32 v25, v24
	v_exp_f32_e32 v18, v18
	v_mul_f32_e32 v19, 0xbfb8aa3b, v19
	v_exp_f32_e32 v19, v19
	v_add_f32_e32 v17, 1.0, v17
	v_rcp_f32_e32 v24, v17
	v_add_f32_e32 v17, 1.0, v25
	v_rcp_f32_e32 v25, v17
	v_add_f32_e32 v17, 1.0, v18
	v_rcp_f32_e32 v26, v17
	v_add_f32_e32 v17, 1.0, v19
	v_rcp_f32_e32 v27, v17
	v_pk_mul_f32 v[18:19], v[32:33], v[24:25]
	v_ashrrev_i32_e32 v49, 31, v48
	v_cvt_pk_bf16_f32 v18, v18, v19
	v_pk_mul_f32 v[20:21], v[20:21], v[26:27]
	s_lshl_b32 s70, s86, 1
	v_cvt_pk_bf16_f32 v19, v20, v21
	v_lshlrev_b64 v[20:21], 10, v[48:49]
	v_lshl_add_u64 v[20:21], s[42:43], 0, v[20:21]
	v_lshl_add_u64 v[20:21], v[20:21], 0, s[22:23]
	s_mov_b32 s71, s23
	v_pk_mul_f32 v[22:23], v[28:29], v[22:23]
	v_lshl_add_u64 v[20:21], v[20:21], 0, s[70:71]
	v_cvt_pk_bf16_f32 v17, v22, v23
	v_lshl_add_u64 v[20:21], v[20:21], 0, v[152:153]
	global_store_dwordx4 v[20:21], v[16:19], off offset:-768

.LBB0_314:
	v_mov_b64_e32 v[12:13], s[76:77]
	v_mad_i64_i32 v[12:13], s[8:9], v32, s92, v[12:13]
	s_or_b32 s8, s22, 0x80
	s_cmp_lt_i32 s8, s89
	s_cselect_b64 s[8:9], -1, 0
	v_cvt_pk_bf16_f32 v22, v24, v25
	v_cvt_pk_bf16_f32 v23, v26, v27
	v_cvt_pk_bf16_f32 v24, v28, v29
	v_cvt_pk_bf16_f32 v25, v30, v31
	v_lshl_add_u64 v[12:13], v[164:165], 1, v[12:13]
	s_and_b64 s[8:9], s[30:31], s[8:9]
	global_store_dwordx4 v[12:13], v[22:25], off
	v_pk_mul_f32 v[28:29], v[2:3], v[8:9]
	s_andn2_b64 vcc, exec, s[8:9]
	v_pk_mul_f32 v[24:25], v[6:7], v[8:9]
	v_pk_mul_f32 v[22:23], v[4:5], v[34:35]
	v_pk_mul_f32 v[26:27], v[0:1], v[34:35]
	s_cbranch_vccnz .LBB0_322
	v_and_b32_e32 v9, 64, v195
	v_xor_b32_e32 v8, 16, v195
	v_add_u32_e32 v9, 64, v9
	v_cmp_lt_i32_e32 vcc, v8, v9
	s_nop 1
	v_cndmask_b32_e32 v8, v195, v8, vcc
	v_lshlrev_b32_e32 v8, 2, v8
	s_waitcnt lgkmcnt(0)
	ds_bpermute_b32 v36, v8, v22
	ds_bpermute_b32 v40, v8, v26
	ds_bpermute_b32 v37, v8, v23
	ds_bpermute_b32 v41, v8, v27
	ds_bpermute_b32 v30, v8, v24
	ds_bpermute_b32 v44, v8, v28
	ds_bpermute_b32 v31, v8, v25
	ds_bpermute_b32 v45, v8, v29
	s_and_saveexec_b64 s[8:9], s[0:1]
	s_cbranch_execz .LBB0_321
	v_lshlrev_b32_e32 v8, 2, v33
	global_load_dwordx4 v[46:49], v8, s[64:65]
	global_load_dwordx4 v[50:53], v8, s[44:45]
	global_load_dwordx4 v[54:57], v8, s[64:65] offset:16
	global_load_dwordx4 v[58:61], v8, s[44:45] offset:16
	s_waitcnt vmcnt(0)
	v_pk_mul_f32 v[8:9], v[24:25], v[48:49]
	v_pk_mul_f32 v[18:19], v[22:23], v[46:47]
	s_waitcnt lgkmcnt(5)
	v_pk_mul_f32 v[38:39], v[50:51], v[36:37]
	s_waitcnt lgkmcnt(1)
	v_pk_mul_f32 v[42:43], v[52:53], v[30:31]
	v_pk_mul_f32 v[30:31], v[28:29], v[56:57]
	v_pk_mul_f32 v[36:37], v[26:27], v[54:55]
	v_pk_mul_f32 v[40:41], v[58:59], v[40:41]
	s_waitcnt lgkmcnt(0)
	v_pk_mul_f32 v[44:45], v[60:61], v[44:45]
	s_and_saveexec_b64 s[10:11], s[4:5]
	s_xor_b64 s[10:11], exec, s[10:11]
	v_pk_add_f32 v[24:25], v[8:9], v[42:43]
	v_pk_add_f32 v[22:23], v[18:19], v[38:39]
	v_pk_add_f32 v[28:29], v[30:31], v[44:45]
	v_pk_add_f32 v[26:27], v[36:37], v[40:41]
	s_andn2_saveexec_b64 s[10:11], s[10:11]
	v_sub_f32_e32 v25, v9, v43
	v_sub_f32_e32 v24, v8, v42
	v_sub_f32_e32 v23, v19, v39
	v_sub_f32_e32 v22, v18, v38
	v_sub_f32_e32 v29, v31, v45
	v_sub_f32_e32 v28, v30, v44
	v_sub_f32_e32 v27, v37, v41
	v_sub_f32_e32 v26, v36, v40
	s_or_b64 exec, exec, s[10:11]

.LBB0_322:
	v_cvt_pk_bf16_f32 v22, v22, v23
	v_cvt_pk_bf16_f32 v23, v24, v25
	v_cvt_pk_bf16_f32 v24, v26, v27
	v_cvt_pk_bf16_f32 v25, v28, v29
	global_store_dwordx4 v[12:13], v[22:25], off offset:256
	s_branch .LBB0_304
.LBB0_323:
	v_pk_mul_f32 v[4:5], v[4:5], v[34:35]
	v_mov_b32_e32 v8, v34
	v_mov_b32_e32 v9, v34
	v_mul_f32_e32 v4, 0xbfb8aa3b, v4
	v_pk_mul_f32 v[12:13], v[14:15], v[8:9]
	v_exp_f32_e32 v14, v4
	v_mul_f32_e32 v4, 0xbfb8aa3b, v5
	v_exp_f32_e32 v15, v4
	v_pk_mul_f32 v[4:5], v[10:11], v[8:9]
	v_add_f32_e32 v10, 1.0, v14
	v_pk_mul_f32 v[6:7], v[6:7], v[8:9]
	v_add_f32_e32 v11, 1.0, v15
	v_rcp_f32_e32 v10, v10
	v_rcp_f32_e32 v11, v11
	v_mul_f32_e32 v6, 0xbfb8aa3b, v6
	v_exp_f32_e32 v6, v6
	v_mul_f32_e32 v7, 0xbfb8aa3b, v7
	v_exp_f32_e32 v7, v7
	v_pk_mul_f32 v[2:3], v[2:3], v[8:9]
	v_pk_mul_f32 v[8:9], v[0:1], v[34:35]
	v_pk_mul_f32 v[0:1], v[20:21], v[10:11]
	v_mul_f32_e32 v2, 0xbfb8aa3b, v2
	v_cvt_pk_bf16_f32 v0, v0, v1
	v_add_f32_e32 v1, 1.0, v6
	v_rcp_f32_e32 v6, v1
	v_add_f32_e32 v1, 1.0, v7
	v_rcp_f32_e32 v7, v1
	v_mul_f32_e32 v1, 0xbfb8aa3b, v8
	v_exp_f32_e32 v1, v1
	v_mul_f32_e32 v8, 0xbfb8aa3b, v9
	v_exp_f32_e32 v9, v8
	v_exp_f32_e32 v2, v2
	v_mul_f32_e32 v3, 0xbfb8aa3b, v3
	v_exp_f32_e32 v3, v3
	v_add_f32_e32 v1, 1.0, v1
	v_rcp_f32_e32 v8, v1
	v_add_f32_e32 v1, 1.0, v9
	v_rcp_f32_e32 v9, v1
	v_add_f32_e32 v1, 1.0, v2
	v_rcp_f32_e32 v10, v1
	v_add_f32_e32 v1, 1.0, v3
	v_rcp_f32_e32 v11, v1
	v_pk_mul_f32 v[2:3], v[16:17], v[8:9]
	v_ashrrev_i32_e32 v33, 31, v32
	v_cvt_pk_bf16_f32 v2, v2, v3
	v_pk_mul_f32 v[4:5], v[4:5], v[10:11]
	v_pk_mul_f32 v[6:7], v[12:13], v[6:7]
	v_cvt_pk_bf16_f32 v3, v4, v5
	v_lshlrev_b64 v[4:5], 10, v[32:33]
	v_lshl_add_u64 v[4:5], s[42:43], 0, v[4:5]
	v_lshl_add_u64 v[4:5], v[4:5], 0, s[22:23]
	s_lshl_b32 s22, s86, 1
	v_lshl_add_u64 v[4:5], v[4:5], 0, s[22:23]
	v_cvt_pk_bf16_f32 v1, v6, v7
	v_lshl_add_u64 v[4:5], v[4:5], 0, v[152:153]
	global_store_dwordx4 v[4:5], v[0:3], off offset:-768
	s_andn2_b64 vcc, exec, s[6:7]
	s_mov_b64 s[6:7], -1
	s_cbranch_vccnz .LBB0_148

.LBB0_890:
	v_lshl_or_b32 v144, s10, 8, v164
	v_cvt_pk_bf16_f32 v124, v124, v125
	v_cvt_pk_bf16_f32 v125, v126, v127
	v_cvt_pk_bf16_f32 v126, v120, v121
	v_mov_b64_e32 v[120:121], s[76:77]
	v_mov_b32_e32 v147, v146
	v_ashrrev_i32_e32 v145, 31, v144
	v_cvt_pk_bf16_f32 v127, v122, v123
	v_mad_i64_i32 v[120:121], s[10:11], v179, s51, v[120:121]
	v_mov_b32_e32 v122, v146
	v_mov_b32_e32 v123, v146
	v_lshl_add_u64 v[120:121], v[144:145], 1, v[120:121]
	v_pk_mul_f32 v[118:119], v[118:119], v[122:123]
	v_pk_mul_f32 v[116:117], v[116:117], v[146:147]
	v_pk_mul_f32 v[114:115], v[114:115], v[122:123]
	s_and_b64 vcc, exec, s[8:9]
	v_pk_mul_f32 v[112:113], v[112:113], v[146:147]
	global_store_dwordx4 v[120:121], v[124:127], off
	s_cbranch_vccnz .LBB0_898
	v_and_b32_e32 v123, 64, v176
	v_xor_b32_e32 v122, 16, v176
	v_add_u32_e32 v123, 64, v123
	v_cmp_lt_i32_e32 vcc, v122, v123
	s_nop 1
	v_cndmask_b32_e32 v122, v176, v122, vcc
	v_lshlrev_b32_e32 v122, 2, v122
	ds_bpermute_b32 v146, v122, v116
	s_waitcnt lgkmcnt(0)
	ds_bpermute_b32 v150, v122, v112
	ds_bpermute_b32 v147, v122, v117
	ds_bpermute_b32 v151, v122, v113
	ds_bpermute_b32 v126, v122, v118
	ds_bpermute_b32 v154, v122, v114
	ds_bpermute_b32 v127, v122, v119
	ds_bpermute_b32 v155, v122, v115
	s_and_saveexec_b64 s[10:11], s[0:1]
	s_cbranch_execz .LBB0_897
	v_lshlrev_b32_e32 v122, 2, v178
	global_load_dwordx4 v[156:159], v122, s[64:65]
	global_load_dwordx4 v[184:187], v122, s[44:45]
	global_load_dwordx4 v[188:191], v122, s[64:65] offset:16
	global_load_dwordx4 v[192:195], v122, s[44:45] offset:16
	s_waitcnt vmcnt(0)
	v_pk_mul_f32 v[122:123], v[118:119], v[158:159]
	v_pk_mul_f32 v[124:125], v[116:117], v[156:157]
	s_waitcnt lgkmcnt(5)
	v_pk_mul_f32 v[148:149], v[184:185], v[146:147]
	s_waitcnt lgkmcnt(1)
	v_pk_mul_f32 v[152:153], v[186:187], v[126:127]
	v_pk_mul_f32 v[126:127], v[114:115], v[190:191]
	v_pk_mul_f32 v[146:147], v[112:113], v[188:189]
	v_pk_mul_f32 v[150:151], v[192:193], v[150:151]
	s_waitcnt lgkmcnt(0)
	v_pk_mul_f32 v[154:155], v[194:195], v[154:155]
	s_and_saveexec_b64 s[30:31], s[4:5]
	s_xor_b64 s[30:31], exec, s[30:31]
	v_pk_add_f32 v[118:119], v[122:123], v[152:153]
	v_pk_add_f32 v[116:117], v[124:125], v[148:149]
	v_pk_add_f32 v[114:115], v[126:127], v[154:155]
	v_pk_add_f32 v[112:113], v[146:147], v[150:151]
	s_andn2_saveexec_b64 s[30:31], s[30:31]
	v_sub_f32_e32 v119, v123, v153
	v_sub_f32_e32 v118, v122, v152
	v_sub_f32_e32 v117, v125, v149
	v_sub_f32_e32 v116, v124, v148
	v_sub_f32_e32 v115, v127, v155
	v_sub_f32_e32 v114, v126, v154
	v_sub_f32_e32 v113, v147, v151
	v_sub_f32_e32 v112, v146, v150
	s_or_b64 exec, exec, s[30:31]

.LBB0_900:
	v_cvt_pk_bf16_f32 v116, v116, v117
	v_cvt_pk_bf16_f32 v117, v118, v119
	v_cvt_pk_bf16_f32 v118, v112, v113
	ds_read_b32 v112, v177 offset:64
	v_add_u32_e32 v149, s21, v165
	v_lshlrev_b32_e32 v113, 3, v149
	v_cvt_pk_bf16_f32 v119, v114, v115
	v_and_b32_e32 v148, 0xfef8, v113
	s_waitcnt lgkmcnt(0)
	v_pk_mul_f32 v[110:111], v[110:111], v[112:113] op_sel_hi:[1,0]
	v_pk_mul_f32 v[108:109], v[108:109], v[112:113] op_sel_hi:[1,0]
	v_pk_mul_f32 v[106:107], v[106:107], v[112:113] op_sel_hi:[1,0]
	s_and_b64 vcc, exec, s[8:9]
	v_pk_mul_f32 v[104:105], v[104:105], v[112:113] op_sel_hi:[1,0]
	global_store_dwordx4 v[120:121], v[116:119], off offset:256
	s_cbranch_vccnz .LBB0_908
	v_and_b32_e32 v114, 64, v176
	v_xor_b32_e32 v113, 16, v176
	v_add_u32_e32 v114, 64, v114
	v_cmp_lt_i32_e32 vcc, v113, v114
	s_nop 1
	v_cndmask_b32_e32 v113, v176, v113, vcc
	v_lshlrev_b32_e32 v113, 2, v113
	ds_bpermute_b32 v120, v113, v108
	ds_bpermute_b32 v124, v113, v104
	ds_bpermute_b32 v121, v113, v109
	ds_bpermute_b32 v125, v113, v105
	ds_bpermute_b32 v118, v113, v110
	ds_bpermute_b32 v146, v113, v106
	ds_bpermute_b32 v119, v113, v111
	ds_bpermute_b32 v147, v113, v107
	s_and_saveexec_b64 s[28:29], s[0:1]
	s_cbranch_execz .LBB0_907
	v_lshlrev_b32_e32 v113, 2, v148
	global_load_dwordx4 v[150:153], v113, s[64:65]
	global_load_dwordx4 v[154:157], v113, s[44:45]
	global_load_dwordx4 v[158:161], v113, s[64:65] offset:16
	global_load_dwordx4 v[184:187], v113, s[44:45] offset:16
	s_waitcnt vmcnt(0)
	v_pk_mul_f32 v[114:115], v[110:111], v[152:153]
	v_pk_mul_f32 v[116:117], v[108:109], v[150:151]
	s_waitcnt lgkmcnt(5)
	v_pk_mul_f32 v[122:123], v[154:155], v[120:121]
	s_waitcnt lgkmcnt(1)
	v_pk_mul_f32 v[126:127], v[156:157], v[118:119]
	v_pk_mul_f32 v[118:119], v[106:107], v[160:161]
	v_pk_mul_f32 v[120:121], v[104:105], v[158:159]
	v_pk_mul_f32 v[124:125], v[184:185], v[124:125]
	s_waitcnt lgkmcnt(0)
	v_pk_mul_f32 v[146:147], v[186:187], v[146:147]
	s_and_saveexec_b64 s[30:31], s[4:5]
	s_xor_b64 s[30:31], exec, s[30:31]
	v_pk_add_f32 v[110:111], v[114:115], v[126:127]
	v_pk_add_f32 v[108:109], v[116:117], v[122:123]
	v_pk_add_f32 v[106:107], v[118:119], v[146:147]
	v_pk_add_f32 v[104:105], v[120:121], v[124:125]
	s_andn2_saveexec_b64 s[30:31], s[30:31]
	v_sub_f32_e32 v111, v115, v127
	v_sub_f32_e32 v110, v114, v126
	v_sub_f32_e32 v109, v117, v123
	v_sub_f32_e32 v108, v116, v122
	v_sub_f32_e32 v107, v119, v147
	v_sub_f32_e32 v106, v118, v146
	v_sub_f32_e32 v105, v121, v125
	v_sub_f32_e32 v104, v120, v124
	s_or_b64 exec, exec, s[30:31]

.LBB0_910:
	v_cvt_pk_bf16_f32 v108, v108, v109
	v_cvt_pk_bf16_f32 v109, v110, v111
	v_cvt_pk_bf16_f32 v110, v104, v105
	v_mov_b64_e32 v[104:105], s[76:77]
	v_mov_b32_e32 v113, v112
	v_cvt_pk_bf16_f32 v111, v106, v107
	v_mad_i64_i32 v[104:105], s[28:29], v149, s51, v[104:105]
	v_mov_b32_e32 v106, v112
	v_mov_b32_e32 v107, v112
	v_lshl_add_u64 v[104:105], v[144:145], 1, v[104:105]
	v_pk_mul_f32 v[102:103], v[102:103], v[106:107]
	v_pk_mul_f32 v[100:101], v[100:101], v[112:113]
	v_pk_mul_f32 v[98:99], v[98:99], v[106:107]
	s_and_b64 vcc, exec, s[8:9]
	v_pk_mul_f32 v[96:97], v[96:97], v[112:113]
	global_store_dwordx4 v[104:105], v[108:111], off
	s_cbranch_vccnz .LBB0_918
	v_and_b32_e32 v107, 64, v176
	v_xor_b32_e32 v106, 16, v176
	v_add_u32_e32 v107, 64, v107
	v_cmp_lt_i32_e32 vcc, v106, v107
	s_nop 1
	v_cndmask_b32_e32 v106, v176, v106, vcc
	v_lshlrev_b32_e32 v106, 2, v106
	ds_bpermute_b32 v112, v106, v100
	ds_bpermute_b32 v116, v106, v96
	ds_bpermute_b32 v113, v106, v101
	ds_bpermute_b32 v117, v106, v97
	ds_bpermute_b32 v110, v106, v102
	s_waitcnt lgkmcnt(0)
	ds_bpermute_b32 v120, v106, v98
	ds_bpermute_b32 v111, v106, v103
	ds_bpermute_b32 v121, v106, v99
	s_and_saveexec_b64 s[28:29], s[0:1]
	s_cbranch_execz .LBB0_917
	v_lshlrev_b32_e32 v106, 2, v148
	global_load_dwordx4 v[122:125], v106, s[64:65]
	global_load_dwordx4 v[146:149], v106, s[44:45]
	global_load_dwordx4 v[150:153], v106, s[64:65] offset:16
	global_load_dwordx4 v[154:157], v106, s[44:45] offset:16
	s_waitcnt vmcnt(0)
	v_pk_mul_f32 v[106:107], v[102:103], v[124:125]
	v_pk_mul_f32 v[108:109], v[100:101], v[122:123]
	v_pk_mul_f32 v[114:115], v[146:147], v[112:113]
	s_waitcnt lgkmcnt(1)
	v_pk_mul_f32 v[118:119], v[148:149], v[110:111]
	v_pk_mul_f32 v[110:111], v[98:99], v[152:153]
	v_pk_mul_f32 v[112:113], v[96:97], v[150:151]
	v_pk_mul_f32 v[116:117], v[154:155], v[116:117]
	s_waitcnt lgkmcnt(0)
	v_pk_mul_f32 v[120:121], v[156:157], v[120:121]
	s_and_saveexec_b64 s[30:31], s[4:5]
	s_xor_b64 s[30:31], exec, s[30:31]
	v_pk_add_f32 v[102:103], v[106:107], v[118:119]
	v_pk_add_f32 v[100:101], v[108:109], v[114:115]
	v_pk_add_f32 v[98:99], v[110:111], v[120:121]
	v_pk_add_f32 v[96:97], v[112:113], v[116:117]
	s_andn2_saveexec_b64 s[30:31], s[30:31]
	v_sub_f32_e32 v103, v107, v119
	v_sub_f32_e32 v102, v106, v118
	v_sub_f32_e32 v101, v109, v115
	v_sub_f32_e32 v100, v108, v114
	v_sub_f32_e32 v99, v111, v121
	v_sub_f32_e32 v98, v110, v120
	v_sub_f32_e32 v97, v113, v117
	v_sub_f32_e32 v96, v112, v116
	s_or_b64 exec, exec, s[30:31]

.LBB0_920:
	v_cvt_pk_bf16_f32 v100, v100, v101
	v_cvt_pk_bf16_f32 v101, v102, v103
	v_cvt_pk_bf16_f32 v102, v96, v97
	ds_read_b32 v96, v177 offset:128
	v_add_u32_e32 v115, s21, v166
	v_lshlrev_b32_e32 v97, 3, v115
	v_cvt_pk_bf16_f32 v103, v98, v99
	v_and_b32_e32 v114, 0xff78, v97
	s_waitcnt lgkmcnt(0)
	v_pk_mul_f32 v[94:95], v[94:95], v[96:97] op_sel_hi:[1,0]
	v_pk_mul_f32 v[92:93], v[92:93], v[96:97] op_sel_hi:[1,0]
	v_pk_mul_f32 v[90:91], v[90:91], v[96:97] op_sel_hi:[1,0]
	s_and_b64 vcc, exec, s[8:9]
	v_pk_mul_f32 v[88:89], v[88:89], v[96:97] op_sel_hi:[1,0]
	global_store_dwordx4 v[104:105], v[100:103], off offset:256
	s_cbranch_vccnz .LBB0_928
	v_and_b32_e32 v98, 64, v176
	v_xor_b32_e32 v97, 16, v176
	v_add_u32_e32 v98, 64, v98
	v_cmp_lt_i32_e32 vcc, v97, v98
	s_nop 1
	v_cndmask_b32_e32 v97, v176, v97, vcc
	v_lshlrev_b32_e32 v97, 2, v97
	ds_bpermute_b32 v104, v97, v92
	ds_bpermute_b32 v108, v97, v88
	ds_bpermute_b32 v105, v97, v93
	ds_bpermute_b32 v109, v97, v89
	ds_bpermute_b32 v102, v97, v94
	ds_bpermute_b32 v112, v97, v90
	ds_bpermute_b32 v103, v97, v95
	ds_bpermute_b32 v113, v97, v91
	s_and_saveexec_b64 s[28:29], s[0:1]
	s_cbranch_execz .LBB0_927
	v_lshlrev_b32_e32 v97, 2, v114
	global_load_dwordx4 v[116:119], v97, s[64:65]
	global_load_dwordx4 v[120:123], v97, s[44:45]
	global_load_dwordx4 v[124:127], v97, s[64:65] offset:16
	global_load_dwordx4 v[146:149], v97, s[44:45] offset:16
	s_waitcnt vmcnt(0)
	v_pk_mul_f32 v[98:99], v[94:95], v[118:119]
	v_pk_mul_f32 v[100:101], v[92:93], v[116:117]
	s_waitcnt lgkmcnt(5)
	v_pk_mul_f32 v[106:107], v[120:121], v[104:105]
	s_waitcnt lgkmcnt(1)
	v_pk_mul_f32 v[110:111], v[122:123], v[102:103]
	v_pk_mul_f32 v[102:103], v[90:91], v[126:127]
	v_pk_mul_f32 v[104:105], v[88:89], v[124:125]
	v_pk_mul_f32 v[108:109], v[146:147], v[108:109]
	s_waitcnt lgkmcnt(0)
	v_pk_mul_f32 v[112:113], v[148:149], v[112:113]
	s_and_saveexec_b64 s[30:31], s[4:5]
	s_xor_b64 s[30:31], exec, s[30:31]
	v_pk_add_f32 v[94:95], v[98:99], v[110:111]
	v_pk_add_f32 v[92:93], v[100:101], v[106:107]
	v_pk_add_f32 v[90:91], v[102:103], v[112:113]
	v_pk_add_f32 v[88:89], v[104:105], v[108:109]
	s_andn2_saveexec_b64 s[30:31], s[30:31]
	v_sub_f32_e32 v95, v99, v111
	v_sub_f32_e32 v94, v98, v110
	v_sub_f32_e32 v93, v101, v107
	v_sub_f32_e32 v92, v100, v106
	v_sub_f32_e32 v91, v103, v113
	v_sub_f32_e32 v90, v102, v112
	v_sub_f32_e32 v89, v105, v109
	v_sub_f32_e32 v88, v104, v108
	s_or_b64 exec, exec, s[30:31]

.LBB0_930:
	v_cvt_pk_bf16_f32 v92, v92, v93
	v_cvt_pk_bf16_f32 v93, v94, v95
	v_cvt_pk_bf16_f32 v94, v88, v89
	v_mov_b64_e32 v[88:89], s[76:77]
	v_mov_b32_e32 v97, v96
	v_cvt_pk_bf16_f32 v95, v90, v91
	v_mad_i64_i32 v[88:89], s[28:29], v115, s51, v[88:89]
	v_mov_b32_e32 v90, v96
	v_mov_b32_e32 v91, v96
	v_lshl_add_u64 v[88:89], v[144:145], 1, v[88:89]
	v_pk_mul_f32 v[86:87], v[86:87], v[90:91]
	v_pk_mul_f32 v[84:85], v[84:85], v[96:97]
	v_pk_mul_f32 v[82:83], v[82:83], v[90:91]
	s_and_b64 vcc, exec, s[8:9]
	v_pk_mul_f32 v[80:81], v[80:81], v[96:97]
	global_store_dwordx4 v[88:89], v[92:95], off
	s_cbranch_vccnz .LBB0_938
	v_and_b32_e32 v91, 64, v176
	v_xor_b32_e32 v90, 16, v176
	v_add_u32_e32 v91, 64, v91
	v_cmp_lt_i32_e32 vcc, v90, v91
	s_nop 1
	v_cndmask_b32_e32 v90, v176, v90, vcc
	v_lshlrev_b32_e32 v90, 2, v90
	ds_bpermute_b32 v96, v90, v84
	ds_bpermute_b32 v100, v90, v80
	ds_bpermute_b32 v97, v90, v85
	ds_bpermute_b32 v101, v90, v81
	ds_bpermute_b32 v94, v90, v86
	s_waitcnt lgkmcnt(0)
	ds_bpermute_b32 v104, v90, v82
	ds_bpermute_b32 v95, v90, v87
	ds_bpermute_b32 v105, v90, v83
	s_and_saveexec_b64 s[28:29], s[0:1]
	s_cbranch_execz .LBB0_937
	v_lshlrev_b32_e32 v90, 2, v114
	global_load_dwordx4 v[106:109], v90, s[64:65]
	global_load_dwordx4 v[110:113], v90, s[44:45]
	global_load_dwordx4 v[114:117], v90, s[64:65] offset:16
	global_load_dwordx4 v[118:121], v90, s[44:45] offset:16
	s_waitcnt vmcnt(0)
	v_pk_mul_f32 v[90:91], v[86:87], v[108:109]
	v_pk_mul_f32 v[92:93], v[84:85], v[106:107]
	v_pk_mul_f32 v[98:99], v[110:111], v[96:97]
	s_waitcnt lgkmcnt(1)
	v_pk_mul_f32 v[102:103], v[112:113], v[94:95]
	v_pk_mul_f32 v[94:95], v[82:83], v[116:117]
	v_pk_mul_f32 v[96:97], v[80:81], v[114:115]
	v_pk_mul_f32 v[100:101], v[118:119], v[100:101]
	s_waitcnt lgkmcnt(0)
	v_pk_mul_f32 v[104:105], v[120:121], v[104:105]
	s_and_saveexec_b64 s[30:31], s[4:5]
	s_xor_b64 s[30:31], exec, s[30:31]
	v_pk_add_f32 v[86:87], v[90:91], v[102:103]
	v_pk_add_f32 v[84:85], v[92:93], v[98:99]
	v_pk_add_f32 v[82:83], v[94:95], v[104:105]
	v_pk_add_f32 v[80:81], v[96:97], v[100:101]
	s_andn2_saveexec_b64 s[30:31], s[30:31]
	v_sub_f32_e32 v87, v91, v103
	v_sub_f32_e32 v86, v90, v102
	v_sub_f32_e32 v85, v93, v99
	v_sub_f32_e32 v84, v92, v98
	v_sub_f32_e32 v83, v95, v105
	v_sub_f32_e32 v82, v94, v104
	v_sub_f32_e32 v81, v97, v101
	v_sub_f32_e32 v80, v96, v100
	s_or_b64 exec, exec, s[30:31]

.LBB0_940:
	v_cvt_pk_bf16_f32 v84, v84, v85
	v_cvt_pk_bf16_f32 v85, v86, v87
	v_cvt_pk_bf16_f32 v86, v80, v81
	ds_read_b32 v80, v177 offset:192
	v_add_u32_e32 v99, s21, v167
	v_lshlrev_b32_e32 v81, 3, v99
	v_cvt_pk_bf16_f32 v87, v82, v83
	v_and_b32_e32 v98, 0xfff8, v81
	s_waitcnt lgkmcnt(0)
	v_pk_mul_f32 v[78:79], v[78:79], v[80:81] op_sel_hi:[1,0]
	v_pk_mul_f32 v[76:77], v[76:77], v[80:81] op_sel_hi:[1,0]
	v_pk_mul_f32 v[74:75], v[74:75], v[80:81] op_sel_hi:[1,0]
	s_and_b64 vcc, exec, s[8:9]
	v_pk_mul_f32 v[72:73], v[72:73], v[80:81] op_sel_hi:[1,0]
	global_store_dwordx4 v[88:89], v[84:87], off offset:256
	s_cbranch_vccnz .LBB0_948
	v_and_b32_e32 v82, 64, v176
	v_xor_b32_e32 v81, 16, v176
	v_add_u32_e32 v82, 64, v82
	v_cmp_lt_i32_e32 vcc, v81, v82
	s_nop 1
	v_cndmask_b32_e32 v81, v176, v81, vcc
	v_lshlrev_b32_e32 v81, 2, v81
	ds_bpermute_b32 v88, v81, v76
	ds_bpermute_b32 v92, v81, v72
	ds_bpermute_b32 v89, v81, v77
	ds_bpermute_b32 v93, v81, v73
	ds_bpermute_b32 v86, v81, v78
	ds_bpermute_b32 v96, v81, v74
	ds_bpermute_b32 v87, v81, v79
	ds_bpermute_b32 v97, v81, v75
	s_and_saveexec_b64 s[28:29], s[0:1]
	s_cbranch_execz .LBB0_947
	v_lshlrev_b32_e32 v81, 2, v98
	global_load_dwordx4 v[100:103], v81, s[64:65]
	global_load_dwordx4 v[104:107], v81, s[44:45]
	global_load_dwordx4 v[108:111], v81, s[64:65] offset:16
	global_load_dwordx4 v[112:115], v81, s[44:45] offset:16
	s_waitcnt vmcnt(0)
	v_pk_mul_f32 v[82:83], v[78:79], v[102:103]
	v_pk_mul_f32 v[84:85], v[76:77], v[100:101]
	s_waitcnt lgkmcnt(5)
	v_pk_mul_f32 v[90:91], v[104:105], v[88:89]
	s_waitcnt lgkmcnt(1)
	v_pk_mul_f32 v[94:95], v[106:107], v[86:87]
	v_pk_mul_f32 v[86:87], v[74:75], v[110:111]
	v_pk_mul_f32 v[88:89], v[72:73], v[108:109]
	v_pk_mul_f32 v[92:93], v[112:113], v[92:93]
	s_waitcnt lgkmcnt(0)
	v_pk_mul_f32 v[96:97], v[114:115], v[96:97]
	s_and_saveexec_b64 s[30:31], s[4:5]
	s_xor_b64 s[30:31], exec, s[30:31]
	v_pk_add_f32 v[78:79], v[82:83], v[94:95]
	v_pk_add_f32 v[76:77], v[84:85], v[90:91]
	v_pk_add_f32 v[74:75], v[86:87], v[96:97]
	v_pk_add_f32 v[72:73], v[88:89], v[92:93]
	s_andn2_saveexec_b64 s[30:31], s[30:31]
	v_sub_f32_e32 v79, v83, v95
	v_sub_f32_e32 v78, v82, v94
	v_sub_f32_e32 v77, v85, v91
	v_sub_f32_e32 v76, v84, v90
	v_sub_f32_e32 v75, v87, v97
	v_sub_f32_e32 v74, v86, v96
	v_sub_f32_e32 v73, v89, v93
	v_sub_f32_e32 v72, v88, v92
	s_or_b64 exec, exec, s[30:31]

.LBB0_950:
	v_cvt_pk_bf16_f32 v76, v76, v77
	v_cvt_pk_bf16_f32 v77, v78, v79
	v_cvt_pk_bf16_f32 v78, v72, v73
	v_mov_b64_e32 v[72:73], s[76:77]
	v_mov_b32_e32 v81, v80
	v_cvt_pk_bf16_f32 v79, v74, v75
	v_mad_i64_i32 v[72:73], s[28:29], v99, s51, v[72:73]
	v_mov_b32_e32 v74, v80
	v_mov_b32_e32 v75, v80
	v_lshl_add_u64 v[72:73], v[144:145], 1, v[72:73]
	v_pk_mul_f32 v[70:71], v[70:71], v[74:75]
	v_pk_mul_f32 v[68:69], v[68:69], v[80:81]
	v_pk_mul_f32 v[66:67], v[66:67], v[74:75]
	s_and_b64 vcc, exec, s[8:9]
	v_pk_mul_f32 v[64:65], v[64:65], v[80:81]
	global_store_dwordx4 v[72:73], v[76:79], off
	s_cbranch_vccnz .LBB0_958
	v_and_b32_e32 v75, 64, v176
	v_xor_b32_e32 v74, 16, v176
	v_add_u32_e32 v75, 64, v75
	v_cmp_lt_i32_e32 vcc, v74, v75
	s_nop 1
	v_cndmask_b32_e32 v74, v176, v74, vcc
	v_lshlrev_b32_e32 v74, 2, v74
	ds_bpermute_b32 v80, v74, v68
	ds_bpermute_b32 v84, v74, v64
	ds_bpermute_b32 v81, v74, v69
	ds_bpermute_b32 v85, v74, v65
	ds_bpermute_b32 v78, v74, v70
	s_waitcnt lgkmcnt(0)
	ds_bpermute_b32 v88, v74, v66
	ds_bpermute_b32 v79, v74, v71
	ds_bpermute_b32 v89, v74, v67
	s_and_saveexec_b64 s[28:29], s[0:1]
	s_cbranch_execz .LBB0_957
	v_lshlrev_b32_e32 v74, 2, v98
	global_load_dwordx4 v[90:93], v74, s[64:65]
	global_load_dwordx4 v[94:97], v74, s[44:45]
	global_load_dwordx4 v[98:101], v74, s[64:65] offset:16
	global_load_dwordx4 v[102:105], v74, s[44:45] offset:16
	s_waitcnt vmcnt(0)
	v_pk_mul_f32 v[74:75], v[70:71], v[92:93]
	v_pk_mul_f32 v[76:77], v[68:69], v[90:91]
	v_pk_mul_f32 v[82:83], v[94:95], v[80:81]
	s_waitcnt lgkmcnt(1)
	v_pk_mul_f32 v[86:87], v[96:97], v[78:79]
	v_pk_mul_f32 v[78:79], v[66:67], v[100:101]
	v_pk_mul_f32 v[80:81], v[64:65], v[98:99]
	v_pk_mul_f32 v[84:85], v[102:103], v[84:85]
	s_waitcnt lgkmcnt(0)
	v_pk_mul_f32 v[88:89], v[104:105], v[88:89]
	s_and_saveexec_b64 s[30:31], s[4:5]
	s_xor_b64 s[30:31], exec, s[30:31]
	v_pk_add_f32 v[70:71], v[74:75], v[86:87]
	v_pk_add_f32 v[68:69], v[76:77], v[82:83]
	v_pk_add_f32 v[66:67], v[78:79], v[88:89]
	v_pk_add_f32 v[64:65], v[80:81], v[84:85]
	s_andn2_saveexec_b64 s[30:31], s[30:31]
	v_sub_f32_e32 v71, v75, v87
	v_sub_f32_e32 v70, v74, v86
	v_sub_f32_e32 v69, v77, v83
	v_sub_f32_e32 v68, v76, v82
	v_sub_f32_e32 v67, v79, v89
	v_sub_f32_e32 v66, v78, v88
	v_sub_f32_e32 v65, v81, v85
	v_sub_f32_e32 v64, v80, v84
	s_or_b64 exec, exec, s[30:31]

.LBB0_960:
	v_cvt_pk_bf16_f32 v68, v68, v69
	v_cvt_pk_bf16_f32 v69, v70, v71
	v_cvt_pk_bf16_f32 v70, v64, v65
	ds_read_b32 v64, v177 offset:512
	v_add_u32_e32 v83, s21, v168
	v_lshlrev_b32_e32 v65, 3, v83
	v_cvt_pk_bf16_f32 v71, v66, v67
	v_and_b32_e32 v82, 0xfe78, v65
	s_waitcnt lgkmcnt(0)
	v_pk_mul_f32 v[62:63], v[62:63], v[64:65] op_sel_hi:[1,0]
	v_pk_mul_f32 v[60:61], v[60:61], v[64:65] op_sel_hi:[1,0]
	v_pk_mul_f32 v[58:59], v[58:59], v[64:65] op_sel_hi:[1,0]
	s_and_b64 vcc, exec, s[8:9]
	v_pk_mul_f32 v[56:57], v[56:57], v[64:65] op_sel_hi:[1,0]
	global_store_dwordx4 v[72:73], v[68:71], off offset:256
	s_cbranch_vccnz .LBB0_968
	v_and_b32_e32 v66, 64, v176
	v_xor_b32_e32 v65, 16, v176
	v_add_u32_e32 v66, 64, v66
	v_cmp_lt_i32_e32 vcc, v65, v66
	s_nop 1
	v_cndmask_b32_e32 v65, v176, v65, vcc
	v_lshlrev_b32_e32 v65, 2, v65
	ds_bpermute_b32 v72, v65, v60
	ds_bpermute_b32 v76, v65, v56
	ds_bpermute_b32 v73, v65, v61
	ds_bpermute_b32 v77, v65, v57
	ds_bpermute_b32 v70, v65, v62
	ds_bpermute_b32 v80, v65, v58
	ds_bpermute_b32 v71, v65, v63
	ds_bpermute_b32 v81, v65, v59
	s_and_saveexec_b64 s[28:29], s[0:1]
	s_cbranch_execz .LBB0_967
	v_lshlrev_b32_e32 v65, 2, v82
	global_load_dwordx4 v[84:87], v65, s[64:65]
	global_load_dwordx4 v[88:91], v65, s[44:45]
	global_load_dwordx4 v[92:95], v65, s[64:65] offset:16
	global_load_dwordx4 v[96:99], v65, s[44:45] offset:16
	s_waitcnt vmcnt(0)
	v_pk_mul_f32 v[66:67], v[62:63], v[86:87]
	v_pk_mul_f32 v[68:69], v[60:61], v[84:85]
	s_waitcnt lgkmcnt(5)
	v_pk_mul_f32 v[74:75], v[88:89], v[72:73]
	s_waitcnt lgkmcnt(1)
	v_pk_mul_f32 v[78:79], v[90:91], v[70:71]
	v_pk_mul_f32 v[70:71], v[58:59], v[94:95]
	v_pk_mul_f32 v[72:73], v[56:57], v[92:93]
	v_pk_mul_f32 v[76:77], v[96:97], v[76:77]
	s_waitcnt lgkmcnt(0)
	v_pk_mul_f32 v[80:81], v[98:99], v[80:81]
	s_and_saveexec_b64 s[30:31], s[4:5]
	s_xor_b64 s[30:31], exec, s[30:31]
	v_pk_add_f32 v[62:63], v[66:67], v[78:79]
	v_pk_add_f32 v[60:61], v[68:69], v[74:75]
	v_pk_add_f32 v[58:59], v[70:71], v[80:81]
	v_pk_add_f32 v[56:57], v[72:73], v[76:77]
	s_andn2_saveexec_b64 s[30:31], s[30:31]
	v_sub_f32_e32 v63, v67, v79
	v_sub_f32_e32 v62, v66, v78
	v_sub_f32_e32 v61, v69, v75
	v_sub_f32_e32 v60, v68, v74
	v_sub_f32_e32 v59, v71, v81
	v_sub_f32_e32 v58, v70, v80
	v_sub_f32_e32 v57, v73, v77
	v_sub_f32_e32 v56, v72, v76
	s_or_b64 exec, exec, s[30:31]

.LBB0_970:
	v_cvt_pk_bf16_f32 v60, v60, v61
	v_cvt_pk_bf16_f32 v61, v62, v63
	v_cvt_pk_bf16_f32 v62, v56, v57
	v_mov_b64_e32 v[56:57], s[76:77]
	v_mov_b32_e32 v65, v64
	v_cvt_pk_bf16_f32 v63, v58, v59
	v_mad_i64_i32 v[56:57], s[28:29], v83, s51, v[56:57]
	v_mov_b32_e32 v58, v64
	v_mov_b32_e32 v59, v64
	v_lshl_add_u64 v[56:57], v[144:145], 1, v[56:57]
	v_pk_mul_f32 v[54:55], v[54:55], v[58:59]
	v_pk_mul_f32 v[52:53], v[52:53], v[64:65]
	v_pk_mul_f32 v[50:51], v[50:51], v[58:59]
	s_and_b64 vcc, exec, s[8:9]
	v_pk_mul_f32 v[48:49], v[48:49], v[64:65]
	global_store_dwordx4 v[56:57], v[60:63], off
	s_cbranch_vccnz .LBB0_978
	v_and_b32_e32 v59, 64, v176
	v_xor_b32_e32 v58, 16, v176
	v_add_u32_e32 v59, 64, v59
	v_cmp_lt_i32_e32 vcc, v58, v59
	s_nop 1
	v_cndmask_b32_e32 v58, v176, v58, vcc
	v_lshlrev_b32_e32 v58, 2, v58
	ds_bpermute_b32 v64, v58, v52
	ds_bpermute_b32 v68, v58, v48
	ds_bpermute_b32 v65, v58, v53
	ds_bpermute_b32 v69, v58, v49
	ds_bpermute_b32 v62, v58, v54
	s_waitcnt lgkmcnt(0)
	ds_bpermute_b32 v72, v58, v50
	ds_bpermute_b32 v63, v58, v55
	ds_bpermute_b32 v73, v58, v51
	s_and_saveexec_b64 s[28:29], s[0:1]
	s_cbranch_execz .LBB0_977
	v_lshlrev_b32_e32 v58, 2, v82
	global_load_dwordx4 v[74:77], v58, s[64:65]
	global_load_dwordx4 v[78:81], v58, s[44:45]
	global_load_dwordx4 v[82:85], v58, s[64:65] offset:16
	global_load_dwordx4 v[86:89], v58, s[44:45] offset:16
	s_waitcnt vmcnt(0)
	v_pk_mul_f32 v[58:59], v[54:55], v[76:77]
	v_pk_mul_f32 v[60:61], v[52:53], v[74:75]
	v_pk_mul_f32 v[66:67], v[78:79], v[64:65]
	s_waitcnt lgkmcnt(1)
	v_pk_mul_f32 v[70:71], v[80:81], v[62:63]
	v_pk_mul_f32 v[62:63], v[50:51], v[84:85]
	v_pk_mul_f32 v[64:65], v[48:49], v[82:83]
	v_pk_mul_f32 v[68:69], v[86:87], v[68:69]
	s_waitcnt lgkmcnt(0)
	v_pk_mul_f32 v[72:73], v[88:89], v[72:73]
	s_and_saveexec_b64 s[30:31], s[4:5]
	s_xor_b64 s[30:31], exec, s[30:31]
	v_pk_add_f32 v[54:55], v[58:59], v[70:71]
	v_pk_add_f32 v[52:53], v[60:61], v[66:67]
	v_pk_add_f32 v[50:51], v[62:63], v[72:73]
	v_pk_add_f32 v[48:49], v[64:65], v[68:69]
	s_andn2_saveexec_b64 s[30:31], s[30:31]
	v_sub_f32_e32 v55, v59, v71
	v_sub_f32_e32 v54, v58, v70
	v_sub_f32_e32 v53, v61, v67
	v_sub_f32_e32 v52, v60, v66
	v_sub_f32_e32 v51, v63, v73
	v_sub_f32_e32 v50, v62, v72
	v_sub_f32_e32 v49, v65, v69
	v_sub_f32_e32 v48, v64, v68
	s_or_b64 exec, exec, s[30:31]

.LBB0_980:
	v_cvt_pk_bf16_f32 v52, v52, v53
	v_cvt_pk_bf16_f32 v53, v54, v55
	v_cvt_pk_bf16_f32 v54, v48, v49
	ds_read_b32 v48, v177 offset:576
	v_add_u32_e32 v67, s21, v169
	v_lshlrev_b32_e32 v49, 3, v67
	v_cvt_pk_bf16_f32 v55, v50, v51
	v_and_b32_e32 v66, 0xfef8, v49
	s_waitcnt lgkmcnt(0)
	v_pk_mul_f32 v[46:47], v[46:47], v[48:49] op_sel_hi:[1,0]
	v_pk_mul_f32 v[44:45], v[44:45], v[48:49] op_sel_hi:[1,0]
	v_pk_mul_f32 v[42:43], v[42:43], v[48:49] op_sel_hi:[1,0]
	s_and_b64 vcc, exec, s[8:9]
	v_pk_mul_f32 v[40:41], v[40:41], v[48:49] op_sel_hi:[1,0]
	global_store_dwordx4 v[56:57], v[52:55], off offset:256
	s_cbranch_vccnz .LBB0_988
	v_and_b32_e32 v50, 64, v176
	v_xor_b32_e32 v49, 16, v176
	v_add_u32_e32 v50, 64, v50
	v_cmp_lt_i32_e32 vcc, v49, v50
	s_nop 1
	v_cndmask_b32_e32 v49, v176, v49, vcc
	v_lshlrev_b32_e32 v49, 2, v49
	ds_bpermute_b32 v56, v49, v44
	ds_bpermute_b32 v60, v49, v40
	ds_bpermute_b32 v57, v49, v45
	ds_bpermute_b32 v61, v49, v41
	ds_bpermute_b32 v54, v49, v46
	ds_bpermute_b32 v64, v49, v42
	ds_bpermute_b32 v55, v49, v47
	ds_bpermute_b32 v65, v49, v43
	s_and_saveexec_b64 s[28:29], s[0:1]
	s_cbranch_execz .LBB0_987
	v_lshlrev_b32_e32 v49, 2, v66
	global_load_dwordx4 v[68:71], v49, s[64:65]
	global_load_dwordx4 v[72:75], v49, s[44:45]
	global_load_dwordx4 v[76:79], v49, s[64:65] offset:16
	global_load_dwordx4 v[80:83], v49, s[44:45] offset:16
	s_waitcnt vmcnt(0)
	v_pk_mul_f32 v[50:51], v[46:47], v[70:71]
	v_pk_mul_f32 v[52:53], v[44:45], v[68:69]
	s_waitcnt lgkmcnt(5)
	v_pk_mul_f32 v[58:59], v[72:73], v[56:57]
	s_waitcnt lgkmcnt(1)
	v_pk_mul_f32 v[62:63], v[74:75], v[54:55]
	v_pk_mul_f32 v[54:55], v[42:43], v[78:79]
	v_pk_mul_f32 v[56:57], v[40:41], v[76:77]
	v_pk_mul_f32 v[60:61], v[80:81], v[60:61]
	s_waitcnt lgkmcnt(0)
	v_pk_mul_f32 v[64:65], v[82:83], v[64:65]
	s_and_saveexec_b64 s[30:31], s[4:5]
	s_xor_b64 s[30:31], exec, s[30:31]
	v_pk_add_f32 v[46:47], v[50:51], v[62:63]
	v_pk_add_f32 v[44:45], v[52:53], v[58:59]
	v_pk_add_f32 v[42:43], v[54:55], v[64:65]
	v_pk_add_f32 v[40:41], v[56:57], v[60:61]
	s_andn2_saveexec_b64 s[30:31], s[30:31]
	v_sub_f32_e32 v47, v51, v63
	v_sub_f32_e32 v46, v50, v62
	v_sub_f32_e32 v45, v53, v59
	v_sub_f32_e32 v44, v52, v58
	v_sub_f32_e32 v43, v55, v65
	v_sub_f32_e32 v42, v54, v64
	v_sub_f32_e32 v41, v57, v61
	v_sub_f32_e32 v40, v56, v60
	s_or_b64 exec, exec, s[30:31]

.LBB0_990:
	v_cvt_pk_bf16_f32 v44, v44, v45
	v_cvt_pk_bf16_f32 v45, v46, v47
	v_cvt_pk_bf16_f32 v46, v40, v41
	v_mov_b64_e32 v[40:41], s[76:77]
	v_mov_b32_e32 v49, v48
	v_cvt_pk_bf16_f32 v47, v42, v43
	v_mad_i64_i32 v[40:41], s[28:29], v67, s51, v[40:41]
	v_mov_b32_e32 v42, v48
	v_mov_b32_e32 v43, v48
	v_lshl_add_u64 v[40:41], v[144:145], 1, v[40:41]
	v_pk_mul_f32 v[38:39], v[38:39], v[42:43]
	v_pk_mul_f32 v[36:37], v[36:37], v[48:49]
	v_pk_mul_f32 v[34:35], v[34:35], v[42:43]
	s_and_b64 vcc, exec, s[8:9]
	v_pk_mul_f32 v[32:33], v[32:33], v[48:49]
	global_store_dwordx4 v[40:41], v[44:47], off
	s_cbranch_vccnz .LBB0_998
	v_and_b32_e32 v43, 64, v176
	v_xor_b32_e32 v42, 16, v176
	v_add_u32_e32 v43, 64, v43
	v_cmp_lt_i32_e32 vcc, v42, v43
	s_nop 1
	v_cndmask_b32_e32 v42, v176, v42, vcc
	v_lshlrev_b32_e32 v42, 2, v42
	ds_bpermute_b32 v48, v42, v36
	ds_bpermute_b32 v52, v42, v32
	ds_bpermute_b32 v49, v42, v37
	ds_bpermute_b32 v53, v42, v33
	ds_bpermute_b32 v46, v42, v38
	s_waitcnt lgkmcnt(0)
	ds_bpermute_b32 v56, v42, v34
	ds_bpermute_b32 v47, v42, v39
	ds_bpermute_b32 v57, v42, v35
	s_and_saveexec_b64 s[28:29], s[0:1]
	s_cbranch_execz .LBB0_997
	v_lshlrev_b32_e32 v42, 2, v66
	global_load_dwordx4 v[58:61], v42, s[64:65]
	global_load_dwordx4 v[62:65], v42, s[44:45]
	global_load_dwordx4 v[66:69], v42, s[64:65] offset:16
	global_load_dwordx4 v[70:73], v42, s[44:45] offset:16
	s_waitcnt vmcnt(0)
	v_pk_mul_f32 v[42:43], v[38:39], v[60:61]
	v_pk_mul_f32 v[44:45], v[36:37], v[58:59]
	v_pk_mul_f32 v[50:51], v[62:63], v[48:49]
	s_waitcnt lgkmcnt(1)
	v_pk_mul_f32 v[54:55], v[64:65], v[46:47]
	v_pk_mul_f32 v[46:47], v[34:35], v[68:69]
	v_pk_mul_f32 v[48:49], v[32:33], v[66:67]
	v_pk_mul_f32 v[52:53], v[70:71], v[52:53]
	s_waitcnt lgkmcnt(0)
	v_pk_mul_f32 v[56:57], v[72:73], v[56:57]
	s_and_saveexec_b64 s[30:31], s[4:5]
	s_xor_b64 s[30:31], exec, s[30:31]
	v_pk_add_f32 v[38:39], v[42:43], v[54:55]
	v_pk_add_f32 v[36:37], v[44:45], v[50:51]
	v_pk_add_f32 v[34:35], v[46:47], v[56:57]
	v_pk_add_f32 v[32:33], v[48:49], v[52:53]
	s_andn2_saveexec_b64 s[30:31], s[30:31]
	v_sub_f32_e32 v39, v43, v55
	v_sub_f32_e32 v38, v42, v54
	v_sub_f32_e32 v37, v45, v51
	v_sub_f32_e32 v36, v44, v50
	v_sub_f32_e32 v35, v47, v57
	v_sub_f32_e32 v34, v46, v56
	v_sub_f32_e32 v33, v49, v53
	v_sub_f32_e32 v32, v48, v52
	s_or_b64 exec, exec, s[30:31]

.LBB0_1000:
	v_cvt_pk_bf16_f32 v36, v36, v37
	v_cvt_pk_bf16_f32 v37, v38, v39
	v_cvt_pk_bf16_f32 v38, v32, v33
	ds_read_b32 v32, v177 offset:640
	v_add_u32_e32 v51, s21, v170
	v_lshlrev_b32_e32 v33, 3, v51
	v_cvt_pk_bf16_f32 v39, v34, v35
	v_and_b32_e32 v50, 0xff78, v33
	s_waitcnt lgkmcnt(0)
	v_pk_mul_f32 v[30:31], v[30:31], v[32:33] op_sel_hi:[1,0]
	v_pk_mul_f32 v[28:29], v[28:29], v[32:33] op_sel_hi:[1,0]
	v_pk_mul_f32 v[26:27], v[26:27], v[32:33] op_sel_hi:[1,0]
	s_and_b64 vcc, exec, s[8:9]
	v_pk_mul_f32 v[24:25], v[24:25], v[32:33] op_sel_hi:[1,0]
	global_store_dwordx4 v[40:41], v[36:39], off offset:256
	s_cbranch_vccnz .LBB0_1008
	v_and_b32_e32 v34, 64, v176
	v_xor_b32_e32 v33, 16, v176
	v_add_u32_e32 v34, 64, v34
	v_cmp_lt_i32_e32 vcc, v33, v34
	s_nop 1
	v_cndmask_b32_e32 v33, v176, v33, vcc
	v_lshlrev_b32_e32 v33, 2, v33
	ds_bpermute_b32 v40, v33, v28
	ds_bpermute_b32 v44, v33, v24
	ds_bpermute_b32 v41, v33, v29
	ds_bpermute_b32 v45, v33, v25
	ds_bpermute_b32 v38, v33, v30
	ds_bpermute_b32 v48, v33, v26
	ds_bpermute_b32 v39, v33, v31
	ds_bpermute_b32 v49, v33, v27
	s_and_saveexec_b64 s[28:29], s[0:1]
	s_cbranch_execz .LBB0_1007
	v_lshlrev_b32_e32 v33, 2, v50
	global_load_dwordx4 v[52:55], v33, s[64:65]
	global_load_dwordx4 v[56:59], v33, s[44:45]
	global_load_dwordx4 v[60:63], v33, s[64:65] offset:16
	global_load_dwordx4 v[64:67], v33, s[44:45] offset:16
	s_waitcnt vmcnt(0)
	v_pk_mul_f32 v[34:35], v[30:31], v[54:55]
	v_pk_mul_f32 v[36:37], v[28:29], v[52:53]
	s_waitcnt lgkmcnt(5)
	v_pk_mul_f32 v[42:43], v[56:57], v[40:41]
	s_waitcnt lgkmcnt(1)
	v_pk_mul_f32 v[46:47], v[58:59], v[38:39]
	v_pk_mul_f32 v[38:39], v[26:27], v[62:63]
	v_pk_mul_f32 v[40:41], v[24:25], v[60:61]
	v_pk_mul_f32 v[44:45], v[64:65], v[44:45]
	s_waitcnt lgkmcnt(0)
	v_pk_mul_f32 v[48:49], v[66:67], v[48:49]
	s_and_saveexec_b64 s[30:31], s[4:5]
	s_xor_b64 s[30:31], exec, s[30:31]
	v_pk_add_f32 v[30:31], v[34:35], v[46:47]
	v_pk_add_f32 v[28:29], v[36:37], v[42:43]
	v_pk_add_f32 v[26:27], v[38:39], v[48:49]
	v_pk_add_f32 v[24:25], v[40:41], v[44:45]
	s_andn2_saveexec_b64 s[30:31], s[30:31]
	v_sub_f32_e32 v31, v35, v47
	v_sub_f32_e32 v30, v34, v46
	v_sub_f32_e32 v29, v37, v43
	v_sub_f32_e32 v28, v36, v42
	v_sub_f32_e32 v27, v39, v49
	v_sub_f32_e32 v26, v38, v48
	v_sub_f32_e32 v25, v41, v45
	v_sub_f32_e32 v24, v40, v44
	s_or_b64 exec, exec, s[30:31]

.LBB0_1010:
	v_cvt_pk_bf16_f32 v28, v28, v29
	v_cvt_pk_bf16_f32 v29, v30, v31
	v_cvt_pk_bf16_f32 v30, v24, v25
	v_mov_b64_e32 v[24:25], s[76:77]
	v_mov_b32_e32 v33, v32
	v_cvt_pk_bf16_f32 v31, v26, v27
	v_mad_i64_i32 v[24:25], s[28:29], v51, s51, v[24:25]
	v_mov_b32_e32 v26, v32
	v_mov_b32_e32 v27, v32
	v_lshl_add_u64 v[24:25], v[144:145], 1, v[24:25]
	v_pk_mul_f32 v[22:23], v[22:23], v[26:27]
	v_pk_mul_f32 v[20:21], v[20:21], v[32:33]
	v_pk_mul_f32 v[18:19], v[18:19], v[26:27]
	s_and_b64 vcc, exec, s[8:9]
	v_pk_mul_f32 v[16:17], v[16:17], v[32:33]
	global_store_dwordx4 v[24:25], v[28:31], off
	s_cbranch_vccnz .LBB0_1018
	v_and_b32_e32 v27, 64, v176
	v_xor_b32_e32 v26, 16, v176
	v_add_u32_e32 v27, 64, v27
	v_cmp_lt_i32_e32 vcc, v26, v27
	s_nop 1
	v_cndmask_b32_e32 v26, v176, v26, vcc
	v_lshlrev_b32_e32 v26, 2, v26
	ds_bpermute_b32 v32, v26, v20
	ds_bpermute_b32 v36, v26, v16
	ds_bpermute_b32 v33, v26, v21
	ds_bpermute_b32 v37, v26, v17
	ds_bpermute_b32 v30, v26, v22
	s_waitcnt lgkmcnt(0)
	ds_bpermute_b32 v40, v26, v18
	ds_bpermute_b32 v31, v26, v23
	ds_bpermute_b32 v41, v26, v19
	s_and_saveexec_b64 s[28:29], s[0:1]
	s_cbranch_execz .LBB0_1017
	v_lshlrev_b32_e32 v26, 2, v50
	global_load_dwordx4 v[42:45], v26, s[64:65]
	global_load_dwordx4 v[46:49], v26, s[44:45]
	global_load_dwordx4 v[50:53], v26, s[64:65] offset:16
	global_load_dwordx4 v[54:57], v26, s[44:45] offset:16
	s_waitcnt vmcnt(0)
	v_pk_mul_f32 v[26:27], v[22:23], v[44:45]
	v_pk_mul_f32 v[28:29], v[20:21], v[42:43]
	v_pk_mul_f32 v[34:35], v[46:47], v[32:33]
	s_waitcnt lgkmcnt(1)
	v_pk_mul_f32 v[38:39], v[48:49], v[30:31]
	v_pk_mul_f32 v[30:31], v[18:19], v[52:53]
	v_pk_mul_f32 v[32:33], v[16:17], v[50:51]
	v_pk_mul_f32 v[36:37], v[54:55], v[36:37]
	s_waitcnt lgkmcnt(0)
	v_pk_mul_f32 v[40:41], v[56:57], v[40:41]
	s_and_saveexec_b64 s[30:31], s[4:5]
	s_xor_b64 s[30:31], exec, s[30:31]
	v_pk_add_f32 v[22:23], v[26:27], v[38:39]
	v_pk_add_f32 v[20:21], v[28:29], v[34:35]
	v_pk_add_f32 v[18:19], v[30:31], v[40:41]
	v_pk_add_f32 v[16:17], v[32:33], v[36:37]
	s_andn2_saveexec_b64 s[30:31], s[30:31]
	v_sub_f32_e32 v23, v27, v39
	v_sub_f32_e32 v22, v26, v38
	v_sub_f32_e32 v21, v29, v35
	v_sub_f32_e32 v20, v28, v34
	v_sub_f32_e32 v19, v31, v41
	v_sub_f32_e32 v18, v30, v40
	v_sub_f32_e32 v17, v33, v37
	v_sub_f32_e32 v16, v32, v36
	s_or_b64 exec, exec, s[30:31]

.LBB0_1020:
	v_cvt_pk_bf16_f32 v20, v20, v21
	v_cvt_pk_bf16_f32 v21, v22, v23
	v_cvt_pk_bf16_f32 v22, v16, v17
	ds_read_b32 v16, v177 offset:704
	v_add_u32_e32 v35, s21, v171
	v_lshlrev_b32_e32 v17, 3, v35
	v_cvt_pk_bf16_f32 v23, v18, v19
	v_and_b32_e32 v34, 0xfff8, v17
	s_waitcnt lgkmcnt(0)
	v_pk_mul_f32 v[14:15], v[14:15], v[16:17] op_sel_hi:[1,0]
	v_pk_mul_f32 v[12:13], v[12:13], v[16:17] op_sel_hi:[1,0]
	v_pk_mul_f32 v[10:11], v[10:11], v[16:17] op_sel_hi:[1,0]
	s_and_b64 vcc, exec, s[8:9]
	v_pk_mul_f32 v[8:9], v[8:9], v[16:17] op_sel_hi:[1,0]
	global_store_dwordx4 v[24:25], v[20:23], off offset:256
	s_cbranch_vccnz .LBB0_1028
	v_and_b32_e32 v18, 64, v176
	v_xor_b32_e32 v17, 16, v176
	v_add_u32_e32 v18, 64, v18
	v_cmp_lt_i32_e32 vcc, v17, v18
	s_nop 1
	v_cndmask_b32_e32 v17, v176, v17, vcc
	v_lshlrev_b32_e32 v17, 2, v17
	ds_bpermute_b32 v24, v17, v12
	ds_bpermute_b32 v28, v17, v8
	ds_bpermute_b32 v25, v17, v13
	ds_bpermute_b32 v29, v17, v9
	ds_bpermute_b32 v22, v17, v14
	ds_bpermute_b32 v32, v17, v10
	ds_bpermute_b32 v23, v17, v15
	ds_bpermute_b32 v33, v17, v11
	s_and_saveexec_b64 s[28:29], s[0:1]
	s_cbranch_execz .LBB0_1027
	v_lshlrev_b32_e32 v17, 2, v34
	global_load_dwordx4 v[36:39], v17, s[64:65]
	global_load_dwordx4 v[40:43], v17, s[44:45]
	global_load_dwordx4 v[44:47], v17, s[64:65] offset:16
	global_load_dwordx4 v[48:51], v17, s[44:45] offset:16
	s_waitcnt vmcnt(0)
	v_pk_mul_f32 v[18:19], v[14:15], v[38:39]
	v_pk_mul_f32 v[20:21], v[12:13], v[36:37]
	s_waitcnt lgkmcnt(5)
	v_pk_mul_f32 v[26:27], v[40:41], v[24:25]
	s_waitcnt lgkmcnt(1)
	v_pk_mul_f32 v[30:31], v[42:43], v[22:23]
	v_pk_mul_f32 v[22:23], v[10:11], v[46:47]
	v_pk_mul_f32 v[24:25], v[8:9], v[44:45]
	v_pk_mul_f32 v[28:29], v[48:49], v[28:29]
	s_waitcnt lgkmcnt(0)
	v_pk_mul_f32 v[32:33], v[50:51], v[32:33]
	s_and_saveexec_b64 s[30:31], s[4:5]
	s_xor_b64 s[30:31], exec, s[30:31]
	v_pk_add_f32 v[14:15], v[18:19], v[30:31]
	v_pk_add_f32 v[12:13], v[20:21], v[26:27]
	v_pk_add_f32 v[10:11], v[22:23], v[32:33]
	v_pk_add_f32 v[8:9], v[24:25], v[28:29]
	s_andn2_saveexec_b64 s[30:31], s[30:31]
	v_sub_f32_e32 v15, v19, v31
	v_sub_f32_e32 v14, v18, v30
	v_sub_f32_e32 v13, v21, v27
	v_sub_f32_e32 v12, v20, v26
	v_sub_f32_e32 v11, v23, v33
	v_sub_f32_e32 v10, v22, v32
	v_sub_f32_e32 v9, v25, v29
	v_sub_f32_e32 v8, v24, v28
	s_or_b64 exec, exec, s[30:31]

.LBB0_1030:
	v_cvt_pk_bf16_f32 v12, v12, v13
	v_cvt_pk_bf16_f32 v13, v14, v15
	v_cvt_pk_bf16_f32 v14, v8, v9
	v_mov_b64_e32 v[8:9], s[76:77]
	v_mov_b32_e32 v17, v16
	v_cvt_pk_bf16_f32 v15, v10, v11
	v_mad_i64_i32 v[8:9], s[28:29], v35, s51, v[8:9]
	v_mov_b32_e32 v10, v16
	v_mov_b32_e32 v11, v16
	v_lshl_add_u64 v[8:9], v[144:145], 1, v[8:9]
	v_pk_mul_f32 v[6:7], v[6:7], v[10:11]
	v_pk_mul_f32 v[4:5], v[4:5], v[16:17]
	v_pk_mul_f32 v[2:3], v[2:3], v[10:11]
	s_and_b64 vcc, exec, s[8:9]
	v_pk_mul_f32 v[0:1], v[0:1], v[16:17]
	global_store_dwordx4 v[8:9], v[12:15], off
	s_cbranch_vccnz .LBB0_1038
	v_and_b32_e32 v11, 64, v176
	v_xor_b32_e32 v10, 16, v176
	v_add_u32_e32 v11, 64, v11
	v_cmp_lt_i32_e32 vcc, v10, v11
	s_nop 1
	v_cndmask_b32_e32 v10, v176, v10, vcc
	v_lshlrev_b32_e32 v10, 2, v10
	ds_bpermute_b32 v16, v10, v4
	ds_bpermute_b32 v20, v10, v0
	ds_bpermute_b32 v17, v10, v5
	ds_bpermute_b32 v21, v10, v1
	ds_bpermute_b32 v14, v10, v6
	s_waitcnt lgkmcnt(0)
	ds_bpermute_b32 v24, v10, v2
	ds_bpermute_b32 v15, v10, v7
	ds_bpermute_b32 v25, v10, v3
	s_and_saveexec_b64 s[8:9], s[0:1]
	s_cbranch_execz .LBB0_1037
	v_lshlrev_b32_e32 v10, 2, v34
	global_load_dwordx4 v[26:29], v10, s[64:65]
	global_load_dwordx4 v[30:33], v10, s[44:45]
	global_load_dwordx4 v[34:37], v10, s[64:65] offset:16
	global_load_dwordx4 v[38:41], v10, s[44:45] offset:16
	s_waitcnt vmcnt(0)
	v_pk_mul_f32 v[10:11], v[6:7], v[28:29]
	v_pk_mul_f32 v[12:13], v[4:5], v[26:27]
	v_pk_mul_f32 v[18:19], v[30:31], v[16:17]
	s_waitcnt lgkmcnt(1)
	v_pk_mul_f32 v[22:23], v[32:33], v[14:15]
	v_pk_mul_f32 v[14:15], v[2:3], v[36:37]
	v_pk_mul_f32 v[16:17], v[0:1], v[34:35]
	v_pk_mul_f32 v[20:21], v[38:39], v[20:21]
	s_waitcnt lgkmcnt(0)
	v_pk_mul_f32 v[24:25], v[40:41], v[24:25]
	s_and_saveexec_b64 s[28:29], s[4:5]
	s_xor_b64 s[28:29], exec, s[28:29]
	v_pk_add_f32 v[6:7], v[10:11], v[22:23]
	v_pk_add_f32 v[4:5], v[12:13], v[18:19]
	v_pk_add_f32 v[2:3], v[14:15], v[24:25]
	v_pk_add_f32 v[0:1], v[16:17], v[20:21]
	s_andn2_saveexec_b64 s[28:29], s[28:29]
	v_sub_f32_e32 v7, v11, v23
	v_sub_f32_e32 v6, v10, v22
	v_sub_f32_e32 v5, v13, v19
	v_sub_f32_e32 v4, v12, v18
	v_sub_f32_e32 v3, v15, v25
	v_sub_f32_e32 v2, v14, v24
	v_sub_f32_e32 v1, v17, v21
	v_sub_f32_e32 v0, v16, v20
	s_or_b64 exec, exec, s[28:29]

.LBB0_1040:
	v_cvt_pk_bf16_f32 v4, v4, v5
	v_cvt_pk_bf16_f32 v5, v6, v7
	v_cvt_pk_bf16_f32 v6, v0, v1
	v_cvt_pk_bf16_f32 v7, v2, v3
	s_andn2_b64 vcc, exec, s[6:7]
	s_mov_b64 s[6:7], -1
	global_store_dwordx4 v[8:9], v[4:7], off offset:256
	s_cbranch_vccnz .LBB0_873
	s_andn2_b64 vcc, exec, s[12:13]
	s_cbranch_vccnz .LBB0_872
	s_barrier
	s_branch .LBB0_872
